# scan 2x16 lane map single-chain dots; lazy softmax rescale (T=4) in diff-attn; silu epilogue uses v_rcp_f32 instead of IEEE div sequence
# speedup vs baseline: 1.0263x; 1.0263x over previous
; __device__ __forceinline__ unsigned pk_bf16(float lo, float hi) { const f32x2 v = {lo, hi}; return __builtin_bit_cast(unsigned, __builtin_convertvector(v, nbf16x2)); }
; __device__ __forceinline__ void st8_bf16(bf16_t* p, const f32x4 a, const f32x4 b) { __builtin_nontemporal_store((u32x4){pk_bf16(a[0], a[1]), pk_bf16(a[2], a[3]), pk_bf16(b[0], b[1]), pk_bf16(b[2], b[3])}, (u32x4*)p); }
; __device__ __forceinline__ void st8_f32(float* p, const f32x4 a, const f32x4 b) { __builtin_nontemporal_store(a, (f32x4*)p); __builtin_nontemporal_store(b, (f32x4*)(p + 4)); }
; __device__ __forceinline__ f32x4 silu4(const f32x4 v) { return (f32x4){v[0] / (1.f + __expf(-v[0])), v[1] / (1.f + __expf(-v[1])), v[2] / (1.f + __expf(-v[2])), v[3] / (1.f + __expf(-v[3]))}; }
;     __device__ __forceinline__ void store8(int row, int col, const f32x4 v, const f32x4 w) const {
;     ...
;         else if (col < RWIN) st8_bf16((bf16_t*)(ws + WS_GATE) + (size_t)row * BR + (col - RWP - 512), silu4(v), silu4(w));
.LBB0_175:
	s_lshl_b32 s29, s8, 8
	s_lshl_b32 s31, s6, 8
	s_add_i32 s29, s29, s54
	v_or_b32_e32 v146, s31, v151
	s_mov_b64 s[38:39], s[12:13]
	s_mov_b64 s[40:41], s[14:15]
	v_or_b32_e32 v148, s29, v154
	v_cmp_lt_i32_e64 s[8:9], s61, v146
	s_and_saveexec_b64 s[6:7], s[8:9]
	s_xor_b64 s[6:7], exec, s[6:7]
	s_cbranch_execz .LBB0_182
	s_cmpk_gt_u32 s31, 0x147f
	s_mov_b64 s[10:11], -1
	s_cbranch_scc0 .LBB0_180
	s_cmpk_gt_u32 s31, 0x1c7f
	s_cbranch_scc1 .LBB0_179
	v_ashrrev_i32_e32 v149, 31, v148
	v_lshlrev_b64 v[158:159], 12, v[148:149]
	v_lshl_add_u64 v[158:159], s[40:41], 0, v[158:159]
	v_mov_b32_e32 v147, v145
	v_lshl_add_u64 v[160:161], v[146:147], 1, v[158:159]
	v_add_co_u32_e32 v160, vcc, 0x15add000, v160
	v_mul_f32_e32 v147, 0xbfb8aa3b, v124
	v_mul_f32_e32 v144, 0xbfb8aa3b, v125
	v_mul_f32_e32 v163, 0xbfb8aa3b, v126
	v_mul_f32_e32 v149, 0xbfb8aa3b, v127
	v_mul_f32_e32 v164, 0xbfb8aa3b, v120
	v_mul_f32_e32 v165, 0xbfb8aa3b, v121
	v_mul_f32_e32 v162, 0xbfb8aa3b, v122
	v_mul_f32_e32 v159, 0xbfb8aa3b, v123
	v_exp_f32_e32 v147, v147
	v_exp_f32_e32 v144, v144
	v_exp_f32_e32 v163, v163
	v_exp_f32_e32 v149, v149
	v_exp_f32_e32 v164, v164
	v_exp_f32_e32 v165, v165
	v_exp_f32_e32 v162, v162
	v_exp_f32_e32 v159, v159
	v_add_f32_e32 v147, 1.0, v147
	v_add_f32_e32 v144, 1.0, v144
	v_add_f32_e32 v163, 1.0, v163
	v_add_f32_e32 v149, 1.0, v149
	v_add_f32_e32 v164, 1.0, v164
	v_add_f32_e32 v165, 1.0, v165
	v_add_f32_e32 v162, 1.0, v162
	v_add_f32_e32 v159, 1.0, v159
	v_rcp_f32_e32 v147, v147
	v_rcp_f32_e32 v144, v144
	v_rcp_f32_e32 v163, v163
	v_rcp_f32_e32 v149, v149
	v_rcp_f32_e32 v164, v164
	v_rcp_f32_e32 v165, v165
	v_rcp_f32_e32 v162, v162
	v_rcp_f32_e32 v159, v159
	v_mul_f32_e32 v147, v124, v147
	v_mul_f32_e32 v144, v125, v144
	v_mul_f32_e32 v163, v126, v163
	v_mul_f32_e32 v149, v127, v149
	v_mul_f32_e32 v164, v120, v164
	v_mul_f32_e32 v165, v121, v165
	v_mul_f32_e32 v162, v122, v162
	v_mul_f32_e32 v159, v123, v159
	v_cvt_pk_bf16_f32 v156, v147, v144
	v_cvt_pk_bf16_f32 v157, v163, v149
	v_cvt_pk_bf16_f32 v158, v164, v165
	v_cvt_pk_bf16_f32 v159, v162, v159
	s_nop 1
	v_addc_co_u32_e32 v161, vcc, 0, v161, vcc
	flat_store_dwordx4 v[160:161], v[156:159] offset:1792 nt

; __device__ __forceinline__ unsigned pk_bf16(float lo, float hi) { const f32x2 v = {lo, hi}; return __builtin_bit_cast(unsigned, __builtin_convertvector(v, nbf16x2)); }
; __device__ __forceinline__ void st8_bf16(bf16_t* p, const f32x4 a, const f32x4 b) { __builtin_nontemporal_store((u32x4){pk_bf16(a[0], a[1]), pk_bf16(a[2], a[3]), pk_bf16(b[0], b[1]), pk_bf16(b[2], b[3])}, (u32x4*)p); }
; __device__ __forceinline__ void st8_f32(float* p, const f32x4 a, const f32x4 b) { __builtin_nontemporal_store(a, (f32x4*)p); __builtin_nontemporal_store(b, (f32x4*)(p + 4)); }
; __device__ __forceinline__ f32x4 silu4(const f32x4 v) { return (f32x4){v[0] / (1.f + __expf(-v[0])), v[1] / (1.f + __expf(-v[1])), v[2] / (1.f + __expf(-v[2])), v[3] / (1.f + __expf(-v[3]))}; }
;     __device__ __forceinline__ void store8(int row, int col, const f32x4 v, const f32x4 w) const {
;     ...
;         else if (col < RWIN) st8_bf16((bf16_t*)(ws + WS_GATE) + (size_t)row * BR + (col - RWP - 512), silu4(v), silu4(w));
.LBB0_184:
	s_or_b64 exec, exec, s[6:7]
	v_or_b32_e32 v120, 16, v148
	s_and_saveexec_b64 s[6:7], s[8:9]
	s_xor_b64 s[6:7], exec, s[6:7]
	s_cbranch_execz .LBB0_191
	s_cmpk_gt_u32 s31, 0x147f
	s_mov_b64 s[10:11], -1
	s_cbranch_scc0 .LBB0_189
	s_cmpk_gt_u32 s31, 0x1c7f
	s_cbranch_scc1 .LBB0_188
	v_ashrrev_i32_e32 v121, 31, v120
	v_lshlrev_b64 v[124:125], 12, v[120:121]
	v_lshl_add_u64 v[124:125], s[40:41], 0, v[124:125]
	v_mov_b32_e32 v144, v146
	v_lshl_add_u64 v[126:127], v[144:145], 1, v[124:125]
	v_add_co_u32_e32 v126, vcc, 0x15add000, v126
	v_mul_f32_e32 v149, 0xbfb8aa3b, v116
	v_mul_f32_e32 v121, 0xbfb8aa3b, v117
	v_mul_f32_e32 v156, 0xbfb8aa3b, v118
	v_mul_f32_e32 v157, 0xbfb8aa3b, v119
	v_mul_f32_e32 v158, 0xbfb8aa3b, v112
	v_mul_f32_e32 v159, 0xbfb8aa3b, v113
	v_mul_f32_e32 v144, 0xbfb8aa3b, v114
	v_mul_f32_e32 v125, 0xbfb8aa3b, v115
	v_exp_f32_e32 v149, v149
	v_exp_f32_e32 v121, v121
	v_exp_f32_e32 v156, v156
	v_exp_f32_e32 v157, v157
	v_exp_f32_e32 v158, v158
	v_exp_f32_e32 v159, v159
	v_exp_f32_e32 v144, v144
	v_exp_f32_e32 v125, v125
	v_add_f32_e32 v149, 1.0, v149
	v_add_f32_e32 v121, 1.0, v121
	v_add_f32_e32 v156, 1.0, v156
	v_add_f32_e32 v157, 1.0, v157
	v_add_f32_e32 v158, 1.0, v158
	v_add_f32_e32 v159, 1.0, v159
	v_add_f32_e32 v144, 1.0, v144
	v_add_f32_e32 v125, 1.0, v125
	v_rcp_f32_e32 v149, v149
	v_rcp_f32_e32 v121, v121
	v_rcp_f32_e32 v156, v156
	v_rcp_f32_e32 v157, v157
	v_rcp_f32_e32 v158, v158
	v_rcp_f32_e32 v159, v159
	v_rcp_f32_e32 v144, v144
	v_rcp_f32_e32 v125, v125
	v_mul_f32_e32 v149, v116, v149
	v_mul_f32_e32 v121, v117, v121
	v_mul_f32_e32 v156, v118, v156
	v_mul_f32_e32 v157, v119, v157
	v_mul_f32_e32 v158, v112, v158
	v_mul_f32_e32 v159, v113, v159
	v_mul_f32_e32 v144, v114, v144
	v_mul_f32_e32 v125, v115, v125
	v_cvt_pk_bf16_f32 v122, v149, v121
	v_cvt_pk_bf16_f32 v123, v156, v157
	v_cvt_pk_bf16_f32 v124, v158, v159
	v_cvt_pk_bf16_f32 v125, v144, v125
	s_nop 1
	v_addc_co_u32_e32 v127, vcc, 0, v127, vcc
	flat_store_dwordx4 v[126:127], v[122:125] offset:1792 nt

; __device__ __forceinline__ unsigned pk_bf16(float lo, float hi) { const f32x2 v = {lo, hi}; return __builtin_bit_cast(unsigned, __builtin_convertvector(v, nbf16x2)); }
; __device__ __forceinline__ void st8_bf16(bf16_t* p, const f32x4 a, const f32x4 b) { __builtin_nontemporal_store((u32x4){pk_bf16(a[0], a[1]), pk_bf16(a[2], a[3]), pk_bf16(b[0], b[1]), pk_bf16(b[2], b[3])}, (u32x4*)p); }
; __device__ __forceinline__ void st8_f32(float* p, const f32x4 a, const f32x4 b) { __builtin_nontemporal_store(a, (f32x4*)p); __builtin_nontemporal_store(b, (f32x4*)(p + 4)); }
; __device__ __forceinline__ f32x4 silu4(const f32x4 v) { return (f32x4){v[0] / (1.f + __expf(-v[0])), v[1] / (1.f + __expf(-v[1])), v[2] / (1.f + __expf(-v[2])), v[3] / (1.f + __expf(-v[3]))}; }
;     __device__ __forceinline__ void store8(int row, int col, const f32x4 v, const f32x4 w) const {
;     ...
;         else if (col < RWIN) st8_bf16((bf16_t*)(ws + WS_GATE) + (size_t)row * BR + (col - RWP - 512), silu4(v), silu4(w));
.LBB0_195:
	s_or_b64 exec, exec, s[10:11]
	v_or_b32_e32 v112, 32, v148
	s_and_saveexec_b64 s[6:7], s[8:9]
	s_xor_b64 s[6:7], exec, s[6:7]
	s_cbranch_execz .LBB0_202
	s_cmpk_gt_u32 s31, 0x147f
	s_mov_b64 s[10:11], -1
	s_cbranch_scc0 .LBB0_200
	s_cmpk_gt_u32 s31, 0x1c7f
	s_cbranch_scc1 .LBB0_199
	v_ashrrev_i32_e32 v113, 31, v112
	v_lshlrev_b64 v[116:117], 12, v[112:113]
	v_lshl_add_u64 v[116:117], s[40:41], 0, v[116:117]
	v_mov_b32_e32 v144, v146
	v_lshl_add_u64 v[118:119], v[144:145], 1, v[116:117]
	v_add_co_u32_e32 v118, vcc, 0x15add000, v118
	v_mul_f32_e32 v122, 0xbfb8aa3b, v108
	v_mul_f32_e32 v113, 0xbfb8aa3b, v109
	v_mul_f32_e32 v124, 0xbfb8aa3b, v110
	v_mul_f32_e32 v125, 0xbfb8aa3b, v111
	v_mul_f32_e32 v126, 0xbfb8aa3b, v104
	v_mul_f32_e32 v127, 0xbfb8aa3b, v105
	v_mul_f32_e32 v123, 0xbfb8aa3b, v106
	v_mul_f32_e32 v117, 0xbfb8aa3b, v107
	v_exp_f32_e32 v122, v122
	v_exp_f32_e32 v113, v113
	v_exp_f32_e32 v124, v124
	v_exp_f32_e32 v125, v125
	v_exp_f32_e32 v126, v126
	v_exp_f32_e32 v127, v127
	v_exp_f32_e32 v123, v123
	v_exp_f32_e32 v117, v117
	v_add_f32_e32 v122, 1.0, v122
	v_add_f32_e32 v113, 1.0, v113
	v_add_f32_e32 v124, 1.0, v124
	v_add_f32_e32 v125, 1.0, v125
	v_add_f32_e32 v126, 1.0, v126
	v_add_f32_e32 v127, 1.0, v127
	v_add_f32_e32 v123, 1.0, v123
	v_add_f32_e32 v117, 1.0, v117
	v_rcp_f32_e32 v122, v122
	v_rcp_f32_e32 v113, v113
	v_rcp_f32_e32 v124, v124
	v_rcp_f32_e32 v125, v125
	v_rcp_f32_e32 v126, v126
	v_rcp_f32_e32 v127, v127
	v_rcp_f32_e32 v123, v123
	v_rcp_f32_e32 v117, v117
	v_mul_f32_e32 v122, v108, v122
	v_mul_f32_e32 v113, v109, v113
	v_mul_f32_e32 v124, v110, v124
	v_mul_f32_e32 v125, v111, v125
	v_mul_f32_e32 v126, v104, v126
	v_mul_f32_e32 v127, v105, v127
	v_mul_f32_e32 v123, v106, v123
	v_mul_f32_e32 v117, v107, v117
	v_cvt_pk_bf16_f32 v114, v122, v113
	v_cvt_pk_bf16_f32 v115, v124, v125
	v_cvt_pk_bf16_f32 v116, v126, v127
	v_cvt_pk_bf16_f32 v117, v123, v117
	s_nop 1
	v_addc_co_u32_e32 v119, vcc, 0, v119, vcc
	flat_store_dwordx4 v[118:119], v[114:117] offset:1792 nt

; __device__ __forceinline__ unsigned pk_bf16(float lo, float hi) { const f32x2 v = {lo, hi}; return __builtin_bit_cast(unsigned, __builtin_convertvector(v, nbf16x2)); }
; __device__ __forceinline__ void st8_bf16(bf16_t* p, const f32x4 a, const f32x4 b) { __builtin_nontemporal_store((u32x4){pk_bf16(a[0], a[1]), pk_bf16(a[2], a[3]), pk_bf16(b[0], b[1]), pk_bf16(b[2], b[3])}, (u32x4*)p); }
; __device__ __forceinline__ void st8_f32(float* p, const f32x4 a, const f32x4 b) { __builtin_nontemporal_store(a, (f32x4*)p); __builtin_nontemporal_store(b, (f32x4*)(p + 4)); }
; __device__ __forceinline__ f32x4 silu4(const f32x4 v) { return (f32x4){v[0] / (1.f + __expf(-v[0])), v[1] / (1.f + __expf(-v[1])), v[2] / (1.f + __expf(-v[2])), v[3] / (1.f + __expf(-v[3]))}; }
;     __device__ __forceinline__ void store8(int row, int col, const f32x4 v, const f32x4 w) const {
;     ...
;         else if (col < RWIN) st8_bf16((bf16_t*)(ws + WS_GATE) + (size_t)row * BR + (col - RWP - 512), silu4(v), silu4(w));
.LBB0_204:
	s_or_b64 exec, exec, s[6:7]
	v_or_b32_e32 v104, 48, v148
	s_and_saveexec_b64 s[6:7], s[8:9]
	s_xor_b64 s[6:7], exec, s[6:7]
	s_cbranch_execz .LBB0_211
	s_cmpk_gt_u32 s31, 0x147f
	s_mov_b64 s[10:11], -1
	s_cbranch_scc0 .LBB0_209
	s_cmpk_gt_u32 s31, 0x1c7f
	s_cbranch_scc1 .LBB0_208
	v_ashrrev_i32_e32 v105, 31, v104
	v_lshlrev_b64 v[108:109], 12, v[104:105]
	v_lshl_add_u64 v[108:109], s[40:41], 0, v[108:109]
	v_mov_b32_e32 v144, v146
	v_lshl_add_u64 v[110:111], v[144:145], 1, v[108:109]
	v_add_co_u32_e32 v110, vcc, 0x15add000, v110
	v_mul_f32_e32 v113, 0xbfb8aa3b, v100
	v_mul_f32_e32 v105, 0xbfb8aa3b, v101
	v_mul_f32_e32 v115, 0xbfb8aa3b, v102
	v_mul_f32_e32 v116, 0xbfb8aa3b, v103
	v_mul_f32_e32 v117, 0xbfb8aa3b, v96
	v_mul_f32_e32 v118, 0xbfb8aa3b, v97
	v_mul_f32_e32 v114, 0xbfb8aa3b, v98
	v_mul_f32_e32 v109, 0xbfb8aa3b, v99
	v_exp_f32_e32 v113, v113
	v_exp_f32_e32 v105, v105
	v_exp_f32_e32 v115, v115
	v_exp_f32_e32 v116, v116
	v_exp_f32_e32 v117, v117
	v_exp_f32_e32 v118, v118
	v_exp_f32_e32 v114, v114
	v_exp_f32_e32 v109, v109
	v_add_f32_e32 v113, 1.0, v113
	v_add_f32_e32 v105, 1.0, v105
	v_add_f32_e32 v115, 1.0, v115
	v_add_f32_e32 v116, 1.0, v116
	v_add_f32_e32 v117, 1.0, v117
	v_add_f32_e32 v118, 1.0, v118
	v_add_f32_e32 v114, 1.0, v114
	v_add_f32_e32 v109, 1.0, v109
	v_rcp_f32_e32 v113, v113
	v_rcp_f32_e32 v105, v105
	v_rcp_f32_e32 v115, v115
	v_rcp_f32_e32 v116, v116
	v_rcp_f32_e32 v117, v117
	v_rcp_f32_e32 v118, v118
	v_rcp_f32_e32 v114, v114
	v_rcp_f32_e32 v109, v109
	v_mul_f32_e32 v113, v100, v113
	v_mul_f32_e32 v105, v101, v105
	v_mul_f32_e32 v115, v102, v115
	v_mul_f32_e32 v116, v103, v116
	v_mul_f32_e32 v117, v96, v117
	v_mul_f32_e32 v118, v97, v118
	v_mul_f32_e32 v114, v98, v114
	v_mul_f32_e32 v109, v99, v109
	v_cvt_pk_bf16_f32 v106, v113, v105
	v_cvt_pk_bf16_f32 v107, v115, v116
	v_cvt_pk_bf16_f32 v108, v117, v118
	v_cvt_pk_bf16_f32 v109, v114, v109
	s_nop 1
	v_addc_co_u32_e32 v111, vcc, 0, v111, vcc
	flat_store_dwordx4 v[110:111], v[106:109] offset:1792 nt

; __device__ __forceinline__ unsigned pk_bf16(float lo, float hi) { const f32x2 v = {lo, hi}; return __builtin_bit_cast(unsigned, __builtin_convertvector(v, nbf16x2)); }
; __device__ __forceinline__ void st8_bf16(bf16_t* p, const f32x4 a, const f32x4 b) { __builtin_nontemporal_store((u32x4){pk_bf16(a[0], a[1]), pk_bf16(a[2], a[3]), pk_bf16(b[0], b[1]), pk_bf16(b[2], b[3])}, (u32x4*)p); }
; __device__ __forceinline__ void st8_f32(float* p, const f32x4 a, const f32x4 b) { __builtin_nontemporal_store(a, (f32x4*)p); __builtin_nontemporal_store(b, (f32x4*)(p + 4)); }
; __device__ __forceinline__ f32x4 silu4(const f32x4 v) { return (f32x4){v[0] / (1.f + __expf(-v[0])), v[1] / (1.f + __expf(-v[1])), v[2] / (1.f + __expf(-v[2])), v[3] / (1.f + __expf(-v[3]))}; }
;     __device__ __forceinline__ void store8(int row, int col, const f32x4 v, const f32x4 w) const {
;     ...
;         else if (col < RWIN) st8_bf16((bf16_t*)(ws + WS_GATE) + (size_t)row * BR + (col - RWP - 512), silu4(v), silu4(w));
.LBB0_229:
	v_cmp_lt_u32_e32 vcc, s62, v96
	s_and_saveexec_b64 s[42:43], vcc
	s_xor_b64 s[42:43], exec, s[42:43]
	s_cbranch_execz .LBB0_233
	v_cmp_gt_u32_e32 vcc, s66, v96
	s_and_saveexec_b64 s[44:45], vcc
	s_cbranch_execz .LBB0_232
	v_ashrrev_i32_e32 v149, 31, v148
	v_lshlrev_b64 v[100:101], 12, v[148:149]
	v_lshl_add_u64 v[100:101], s[40:41], 0, v[100:101]
	v_mov_b32_e32 v144, v146
	v_lshl_add_u64 v[102:103], v[144:145], 1, v[100:101]
	v_add_co_u32_e32 v102, vcc, 0x15add000, v102
	v_mul_f32_e32 v105, 0xbfb8aa3b, v92
	v_mul_f32_e32 v97, 0xbfb8aa3b, v93
	v_mul_f32_e32 v107, 0xbfb8aa3b, v94
	v_mul_f32_e32 v108, 0xbfb8aa3b, v95
	v_mul_f32_e32 v109, 0xbfb8aa3b, v88
	v_mul_f32_e32 v110, 0xbfb8aa3b, v89
	v_mul_f32_e32 v106, 0xbfb8aa3b, v90
	v_mul_f32_e32 v101, 0xbfb8aa3b, v91
	v_exp_f32_e32 v105, v105
	v_exp_f32_e32 v97, v97
	v_exp_f32_e32 v107, v107
	v_exp_f32_e32 v108, v108
	v_exp_f32_e32 v109, v109
	v_exp_f32_e32 v110, v110
	v_exp_f32_e32 v106, v106
	v_exp_f32_e32 v101, v101
	v_add_f32_e32 v105, 1.0, v105
	v_add_f32_e32 v97, 1.0, v97
	v_add_f32_e32 v107, 1.0, v107
	v_add_f32_e32 v108, 1.0, v108
	v_add_f32_e32 v109, 1.0, v109
	v_add_f32_e32 v110, 1.0, v110
	v_add_f32_e32 v106, 1.0, v106
	v_add_f32_e32 v101, 1.0, v101
	v_rcp_f32_e32 v105, v105
	v_rcp_f32_e32 v97, v97
	v_rcp_f32_e32 v107, v107
	v_rcp_f32_e32 v108, v108
	v_rcp_f32_e32 v109, v109
	v_rcp_f32_e32 v110, v110
	v_rcp_f32_e32 v106, v106
	v_rcp_f32_e32 v101, v101
	v_mul_f32_e32 v105, v92, v105
	v_mul_f32_e32 v97, v93, v97
	v_mul_f32_e32 v107, v94, v107
	v_mul_f32_e32 v108, v95, v108
	v_mul_f32_e32 v109, v88, v109
	v_mul_f32_e32 v110, v89, v110
	v_mul_f32_e32 v106, v90, v106
	v_mul_f32_e32 v101, v91, v101
	v_cvt_pk_bf16_f32 v98, v105, v97
	v_cvt_pk_bf16_f32 v99, v107, v108
	v_cvt_pk_bf16_f32 v100, v109, v110
	v_cvt_pk_bf16_f32 v101, v106, v101
	s_nop 1
	v_addc_co_u32_e32 v103, vcc, 0, v103, vcc
	flat_store_dwordx4 v[102:103], v[98:101] offset:2048 nt

; __device__ __forceinline__ unsigned pk_bf16(float lo, float hi) { const f32x2 v = {lo, hi}; return __builtin_bit_cast(unsigned, __builtin_convertvector(v, nbf16x2)); }
; __device__ __forceinline__ void st8_bf16(bf16_t* p, const f32x4 a, const f32x4 b) { __builtin_nontemporal_store((u32x4){pk_bf16(a[0], a[1]), pk_bf16(a[2], a[3]), pk_bf16(b[0], b[1]), pk_bf16(b[2], b[3])}, (u32x4*)p); }
; __device__ __forceinline__ void st8_f32(float* p, const f32x4 a, const f32x4 b) { __builtin_nontemporal_store(a, (f32x4*)p); __builtin_nontemporal_store(b, (f32x4*)(p + 4)); }
; __device__ __forceinline__ f32x4 silu4(const f32x4 v) { return (f32x4){v[0] / (1.f + __expf(-v[0])), v[1] / (1.f + __expf(-v[1])), v[2] / (1.f + __expf(-v[2])), v[3] / (1.f + __expf(-v[3]))}; }
;     __device__ __forceinline__ void store8(int row, int col, const f32x4 v, const f32x4 w) const {
;     ...
;         else if (col < RWIN) st8_bf16((bf16_t*)(ws + WS_GATE) + (size_t)row * BR + (col - RWP - 512), silu4(v), silu4(w));
.LBB0_237:
	v_cmp_lt_u32_e32 vcc, s62, v96
	s_and_saveexec_b64 s[42:43], vcc
	s_xor_b64 s[42:43], exec, s[42:43]
	s_cbranch_execz .LBB0_241
	v_cmp_gt_u32_e32 vcc, s66, v96
	s_and_saveexec_b64 s[44:45], vcc
	s_cbranch_execz .LBB0_240
	v_ashrrev_i32_e32 v121, 31, v120
	v_lshlrev_b64 v[90:91], 12, v[120:121]
	v_lshl_add_u64 v[90:91], s[40:41], 0, v[90:91]
	v_mov_b32_e32 v144, v146
	v_lshl_add_u64 v[92:93], v[144:145], 1, v[90:91]
	v_add_co_u32_e32 v92, vcc, 0x15add000, v92
	v_mul_f32_e32 v97, 0xbfb8aa3b, v84
	v_mul_f32_e32 v95, 0xbfb8aa3b, v85
	v_mul_f32_e32 v98, 0xbfb8aa3b, v86
	v_mul_f32_e32 v99, 0xbfb8aa3b, v87
	v_mul_f32_e32 v100, 0xbfb8aa3b, v80
	v_mul_f32_e32 v101, 0xbfb8aa3b, v81
	v_mul_f32_e32 v94, 0xbfb8aa3b, v82
	v_mul_f32_e32 v91, 0xbfb8aa3b, v83
	v_exp_f32_e32 v97, v97
	v_exp_f32_e32 v95, v95
	v_exp_f32_e32 v98, v98
	v_exp_f32_e32 v99, v99
	v_exp_f32_e32 v100, v100
	v_exp_f32_e32 v101, v101
	v_exp_f32_e32 v94, v94
	v_exp_f32_e32 v91, v91
	v_add_f32_e32 v97, 1.0, v97
	v_add_f32_e32 v95, 1.0, v95
	v_add_f32_e32 v98, 1.0, v98
	v_add_f32_e32 v99, 1.0, v99
	v_add_f32_e32 v100, 1.0, v100
	v_add_f32_e32 v101, 1.0, v101
	v_add_f32_e32 v94, 1.0, v94
	v_add_f32_e32 v91, 1.0, v91
	v_rcp_f32_e32 v97, v97
	v_rcp_f32_e32 v95, v95
	v_rcp_f32_e32 v98, v98
	v_rcp_f32_e32 v99, v99
	v_rcp_f32_e32 v100, v100
	v_rcp_f32_e32 v101, v101
	v_rcp_f32_e32 v94, v94
	v_rcp_f32_e32 v91, v91
	v_mul_f32_e32 v97, v84, v97
	v_mul_f32_e32 v95, v85, v95
	v_mul_f32_e32 v98, v86, v98
	v_mul_f32_e32 v99, v87, v99
	v_mul_f32_e32 v100, v80, v100
	v_mul_f32_e32 v101, v81, v101
	v_mul_f32_e32 v94, v82, v94
	v_mul_f32_e32 v91, v83, v91
	v_cvt_pk_bf16_f32 v88, v97, v95
	v_cvt_pk_bf16_f32 v89, v98, v99
	v_cvt_pk_bf16_f32 v90, v100, v101
	v_cvt_pk_bf16_f32 v91, v94, v91
	s_nop 1
	v_addc_co_u32_e32 v93, vcc, 0, v93, vcc
	flat_store_dwordx4 v[92:93], v[88:91] offset:2048 nt

; __device__ __forceinline__ unsigned pk_bf16(float lo, float hi) { const f32x2 v = {lo, hi}; return __builtin_bit_cast(unsigned, __builtin_convertvector(v, nbf16x2)); }
; __device__ __forceinline__ void st8_bf16(bf16_t* p, const f32x4 a, const f32x4 b) { __builtin_nontemporal_store((u32x4){pk_bf16(a[0], a[1]), pk_bf16(a[2], a[3]), pk_bf16(b[0], b[1]), pk_bf16(b[2], b[3])}, (u32x4*)p); }
; __device__ __forceinline__ void st8_f32(float* p, const f32x4 a, const f32x4 b) { __builtin_nontemporal_store(a, (f32x4*)p); __builtin_nontemporal_store(b, (f32x4*)(p + 4)); }
; __device__ __forceinline__ f32x4 silu4(const f32x4 v) { return (f32x4){v[0] / (1.f + __expf(-v[0])), v[1] / (1.f + __expf(-v[1])), v[2] / (1.f + __expf(-v[2])), v[3] / (1.f + __expf(-v[3]))}; }
;     __device__ __forceinline__ void store8(int row, int col, const f32x4 v, const f32x4 w) const {
;     ...
;         else if (col < RWIN) st8_bf16((bf16_t*)(ws + WS_GATE) + (size_t)row * BR + (col - RWP - 512), silu4(v), silu4(w));
.LBB0_247:
	v_cmp_lt_u32_e32 vcc, s62, v96
	s_and_saveexec_b64 s[42:43], vcc
	s_xor_b64 s[42:43], exec, s[42:43]
	s_cbranch_execz .LBB0_251
	v_cmp_gt_u32_e32 vcc, s66, v96
	s_and_saveexec_b64 s[44:45], vcc
	s_cbranch_execz .LBB0_250
	v_ashrrev_i32_e32 v113, 31, v112
	v_lshlrev_b64 v[82:83], 12, v[112:113]
	v_lshl_add_u64 v[82:83], s[40:41], 0, v[82:83]
	v_mov_b32_e32 v144, v146
	v_lshl_add_u64 v[84:85], v[144:145], 1, v[82:83]
	v_add_co_u32_e32 v84, vcc, 0x15add000, v84
	v_mul_f32_e32 v88, 0xbfb8aa3b, v76
	v_mul_f32_e32 v87, 0xbfb8aa3b, v77
	v_mul_f32_e32 v89, 0xbfb8aa3b, v78
	v_mul_f32_e32 v90, 0xbfb8aa3b, v79
	v_mul_f32_e32 v91, 0xbfb8aa3b, v72
	v_mul_f32_e32 v92, 0xbfb8aa3b, v73
	v_mul_f32_e32 v86, 0xbfb8aa3b, v74
	v_mul_f32_e32 v83, 0xbfb8aa3b, v75
	v_exp_f32_e32 v88, v88
	v_exp_f32_e32 v87, v87
	v_exp_f32_e32 v89, v89
	v_exp_f32_e32 v90, v90
	v_exp_f32_e32 v91, v91
	v_exp_f32_e32 v92, v92
	v_exp_f32_e32 v86, v86
	v_exp_f32_e32 v83, v83
	v_add_f32_e32 v88, 1.0, v88
	v_add_f32_e32 v87, 1.0, v87
	v_add_f32_e32 v89, 1.0, v89
	v_add_f32_e32 v90, 1.0, v90
	v_add_f32_e32 v91, 1.0, v91
	v_add_f32_e32 v92, 1.0, v92
	v_add_f32_e32 v86, 1.0, v86
	v_add_f32_e32 v83, 1.0, v83
	v_rcp_f32_e32 v88, v88
	v_rcp_f32_e32 v87, v87
	v_rcp_f32_e32 v89, v89
	v_rcp_f32_e32 v90, v90
	v_rcp_f32_e32 v91, v91
	v_rcp_f32_e32 v92, v92
	v_rcp_f32_e32 v86, v86
	v_rcp_f32_e32 v83, v83
	v_mul_f32_e32 v88, v76, v88
	v_mul_f32_e32 v87, v77, v87
	v_mul_f32_e32 v89, v78, v89
	v_mul_f32_e32 v90, v79, v90
	v_mul_f32_e32 v91, v72, v91
	v_mul_f32_e32 v92, v73, v92
	v_mul_f32_e32 v86, v74, v86
	v_mul_f32_e32 v83, v75, v83
	v_cvt_pk_bf16_f32 v80, v88, v87
	v_cvt_pk_bf16_f32 v81, v89, v90
	v_cvt_pk_bf16_f32 v82, v91, v92
	v_cvt_pk_bf16_f32 v83, v86, v83
	s_nop 1
	v_addc_co_u32_e32 v85, vcc, 0, v85, vcc
	flat_store_dwordx4 v[84:85], v[80:83] offset:2048 nt

; __device__ __forceinline__ unsigned pk_bf16(float lo, float hi) { const f32x2 v = {lo, hi}; return __builtin_bit_cast(unsigned, __builtin_convertvector(v, nbf16x2)); }
; __device__ __forceinline__ void st8_bf16(bf16_t* p, const f32x4 a, const f32x4 b) { __builtin_nontemporal_store((u32x4){pk_bf16(a[0], a[1]), pk_bf16(a[2], a[3]), pk_bf16(b[0], b[1]), pk_bf16(b[2], b[3])}, (u32x4*)p); }
; __device__ __forceinline__ void st8_f32(float* p, const f32x4 a, const f32x4 b) { __builtin_nontemporal_store(a, (f32x4*)p); __builtin_nontemporal_store(b, (f32x4*)(p + 4)); }
; __device__ __forceinline__ f32x4 silu4(const f32x4 v) { return (f32x4){v[0] / (1.f + __expf(-v[0])), v[1] / (1.f + __expf(-v[1])), v[2] / (1.f + __expf(-v[2])), v[3] / (1.f + __expf(-v[3]))}; }
;     __device__ __forceinline__ void store8(int row, int col, const f32x4 v, const f32x4 w) const {
;     ...
;         else if (col < RWIN) st8_bf16((bf16_t*)(ws + WS_GATE) + (size_t)row * BR + (col - RWP - 512), silu4(v), silu4(w));
.LBB0_255:
	v_cmp_lt_u32_e32 vcc, s62, v96
	s_and_saveexec_b64 s[42:43], vcc
	s_xor_b64 s[42:43], exec, s[42:43]
	s_cbranch_execz .LBB0_259
	v_cmp_gt_u32_e32 vcc, s66, v96
	s_and_saveexec_b64 s[44:45], vcc
	s_cbranch_execz .LBB0_258
	v_ashrrev_i32_e32 v105, 31, v104
	v_lshlrev_b64 v[74:75], 12, v[104:105]
	v_lshl_add_u64 v[74:75], s[40:41], 0, v[74:75]
	v_mov_b32_e32 v144, v146
	v_lshl_add_u64 v[76:77], v[144:145], 1, v[74:75]
	v_add_co_u32_e32 v76, vcc, 0x15add000, v76
	v_mul_f32_e32 v80, 0xbfb8aa3b, v68
	v_mul_f32_e32 v79, 0xbfb8aa3b, v69
	v_mul_f32_e32 v81, 0xbfb8aa3b, v70
	v_mul_f32_e32 v82, 0xbfb8aa3b, v71
	v_mul_f32_e32 v83, 0xbfb8aa3b, v64
	v_mul_f32_e32 v84, 0xbfb8aa3b, v65
	v_mul_f32_e32 v78, 0xbfb8aa3b, v66
	v_mul_f32_e32 v75, 0xbfb8aa3b, v67
	v_exp_f32_e32 v80, v80
	v_exp_f32_e32 v79, v79
	v_exp_f32_e32 v81, v81
	v_exp_f32_e32 v82, v82
	v_exp_f32_e32 v83, v83
	v_exp_f32_e32 v84, v84
	v_exp_f32_e32 v78, v78
	v_exp_f32_e32 v75, v75
	v_add_f32_e32 v80, 1.0, v80
	v_add_f32_e32 v79, 1.0, v79
	v_add_f32_e32 v81, 1.0, v81
	v_add_f32_e32 v82, 1.0, v82
	v_add_f32_e32 v83, 1.0, v83
	v_add_f32_e32 v84, 1.0, v84
	v_add_f32_e32 v78, 1.0, v78
	v_add_f32_e32 v75, 1.0, v75
	v_rcp_f32_e32 v80, v80
	v_rcp_f32_e32 v79, v79
	v_rcp_f32_e32 v81, v81
	v_rcp_f32_e32 v82, v82
	v_rcp_f32_e32 v83, v83
	v_rcp_f32_e32 v84, v84
	v_rcp_f32_e32 v78, v78
	v_rcp_f32_e32 v75, v75
	v_mul_f32_e32 v80, v68, v80
	v_mul_f32_e32 v79, v69, v79
	v_mul_f32_e32 v81, v70, v81
	v_mul_f32_e32 v82, v71, v82
	v_mul_f32_e32 v83, v64, v83
	v_mul_f32_e32 v84, v65, v84
	v_mul_f32_e32 v78, v66, v78
	v_mul_f32_e32 v75, v67, v75
	v_cvt_pk_bf16_f32 v72, v80, v79
	v_cvt_pk_bf16_f32 v73, v81, v82
	v_cvt_pk_bf16_f32 v74, v83, v84
	v_cvt_pk_bf16_f32 v75, v78, v75
	s_nop 1
	v_addc_co_u32_e32 v77, vcc, 0, v77, vcc
	flat_store_dwordx4 v[76:77], v[72:75] offset:2048 nt

; __device__ __forceinline__ unsigned pk_bf16(float lo, float hi) { const f32x2 v = {lo, hi}; return __builtin_bit_cast(unsigned, __builtin_convertvector(v, nbf16x2)); }
; __device__ __forceinline__ void st8_bf16(bf16_t* p, const f32x4 a, const f32x4 b) { __builtin_nontemporal_store((u32x4){pk_bf16(a[0], a[1]), pk_bf16(a[2], a[3]), pk_bf16(b[0], b[1]), pk_bf16(b[2], b[3])}, (u32x4*)p); }
; __device__ __forceinline__ void st8_f32(float* p, const f32x4 a, const f32x4 b) { __builtin_nontemporal_store(a, (f32x4*)p); __builtin_nontemporal_store(b, (f32x4*)(p + 4)); }
; __device__ __forceinline__ f32x4 silu4(const f32x4 v) { return (f32x4){v[0] / (1.f + __expf(-v[0])), v[1] / (1.f + __expf(-v[1])), v[2] / (1.f + __expf(-v[2])), v[3] / (1.f + __expf(-v[3]))}; }
;     __device__ __forceinline__ void store8(int row, int col, const f32x4 v, const f32x4 w) const {
;     ...
;         else if (col < RWIN) st8_bf16((bf16_t*)(ws + WS_GATE) + (size_t)row * BR + (col - RWP - 512), silu4(v), silu4(w));
.LBB0_271:
	s_or_b64 exec, exec, s[10:11]
	v_add_u32_e32 v64, 0x80, v148
	s_and_saveexec_b64 s[10:11], s[8:9]
	s_xor_b64 s[10:11], exec, s[10:11]
	s_cbranch_execz .LBB0_278
	s_cmpk_gt_u32 s31, 0x147f
	s_mov_b64 s[42:43], -1
	s_cbranch_scc0 .LBB0_276
	s_cmpk_gt_u32 s31, 0x1c7f
	s_cbranch_scc1 .LBB0_275
	v_ashrrev_i32_e32 v65, 31, v64
	v_lshlrev_b64 v[68:69], 12, v[64:65]
	v_lshl_add_u64 v[68:69], s[40:41], 0, v[68:69]
	v_mov_b32_e32 v144, v146
	v_lshl_add_u64 v[70:71], v[144:145], 1, v[68:69]
	v_add_co_u32_e32 v70, vcc, 0x15add000, v70
	v_mul_f32_e32 v72, 0xbfb8aa3b, v60
	v_mul_f32_e32 v65, 0xbfb8aa3b, v61
	v_mul_f32_e32 v74, 0xbfb8aa3b, v62
	v_mul_f32_e32 v75, 0xbfb8aa3b, v63
	v_mul_f32_e32 v76, 0xbfb8aa3b, v56
	v_mul_f32_e32 v77, 0xbfb8aa3b, v57
	v_mul_f32_e32 v73, 0xbfb8aa3b, v58
	v_mul_f32_e32 v69, 0xbfb8aa3b, v59
	v_exp_f32_e32 v72, v72
	v_exp_f32_e32 v65, v65
	v_exp_f32_e32 v74, v74
	v_exp_f32_e32 v75, v75
	v_exp_f32_e32 v76, v76
	v_exp_f32_e32 v77, v77
	v_exp_f32_e32 v73, v73
	v_exp_f32_e32 v69, v69
	v_add_f32_e32 v72, 1.0, v72
	v_add_f32_e32 v65, 1.0, v65
	v_add_f32_e32 v74, 1.0, v74
	v_add_f32_e32 v75, 1.0, v75
	v_add_f32_e32 v76, 1.0, v76
	v_add_f32_e32 v77, 1.0, v77
	v_add_f32_e32 v73, 1.0, v73
	v_add_f32_e32 v69, 1.0, v69
	v_rcp_f32_e32 v72, v72
	v_rcp_f32_e32 v65, v65
	v_rcp_f32_e32 v74, v74
	v_rcp_f32_e32 v75, v75
	v_rcp_f32_e32 v76, v76
	v_rcp_f32_e32 v77, v77
	v_rcp_f32_e32 v73, v73
	v_rcp_f32_e32 v69, v69
	v_mul_f32_e32 v72, v60, v72
	v_mul_f32_e32 v65, v61, v65
	v_mul_f32_e32 v74, v62, v74
	v_mul_f32_e32 v75, v63, v75
	v_mul_f32_e32 v76, v56, v76
	v_mul_f32_e32 v77, v57, v77
	v_mul_f32_e32 v73, v58, v73
	v_mul_f32_e32 v69, v59, v69
	v_cvt_pk_bf16_f32 v66, v72, v65
	v_cvt_pk_bf16_f32 v67, v74, v75
	v_cvt_pk_bf16_f32 v68, v76, v77
	v_cvt_pk_bf16_f32 v69, v73, v69
	s_nop 1
	v_addc_co_u32_e32 v71, vcc, 0, v71, vcc
	flat_store_dwordx4 v[70:71], v[66:69] offset:1792 nt

; __device__ __forceinline__ unsigned pk_bf16(float lo, float hi) { const f32x2 v = {lo, hi}; return __builtin_bit_cast(unsigned, __builtin_convertvector(v, nbf16x2)); }
; __device__ __forceinline__ void st8_bf16(bf16_t* p, const f32x4 a, const f32x4 b) { __builtin_nontemporal_store((u32x4){pk_bf16(a[0], a[1]), pk_bf16(a[2], a[3]), pk_bf16(b[0], b[1]), pk_bf16(b[2], b[3])}, (u32x4*)p); }
; __device__ __forceinline__ void st8_f32(float* p, const f32x4 a, const f32x4 b) { __builtin_nontemporal_store(a, (f32x4*)p); __builtin_nontemporal_store(b, (f32x4*)(p + 4)); }
; __device__ __forceinline__ f32x4 silu4(const f32x4 v) { return (f32x4){v[0] / (1.f + __expf(-v[0])), v[1] / (1.f + __expf(-v[1])), v[2] / (1.f + __expf(-v[2])), v[3] / (1.f + __expf(-v[3]))}; }
;     __device__ __forceinline__ void store8(int row, int col, const f32x4 v, const f32x4 w) const {
;     ...
;         else if (col < RWIN) st8_bf16((bf16_t*)(ws + WS_GATE) + (size_t)row * BR + (col - RWP - 512), silu4(v), silu4(w));
.LBB0_280:
	s_or_b64 exec, exec, s[10:11]
	v_add_u32_e32 v56, 0x90, v148
	s_and_saveexec_b64 s[10:11], s[8:9]
	s_xor_b64 s[10:11], exec, s[10:11]
	s_cbranch_execz .LBB0_287
	s_cmpk_gt_u32 s31, 0x147f
	s_mov_b64 s[42:43], -1
	s_cbranch_scc0 .LBB0_285
	s_cmpk_gt_u32 s31, 0x1c7f
	s_cbranch_scc1 .LBB0_284
	v_ashrrev_i32_e32 v57, 31, v56
	v_lshlrev_b64 v[60:61], 12, v[56:57]
	v_lshl_add_u64 v[60:61], s[40:41], 0, v[60:61]
	v_mov_b32_e32 v144, v146
	v_lshl_add_u64 v[62:63], v[144:145], 1, v[60:61]
	v_add_co_u32_e32 v62, vcc, 0x15add000, v62
	v_mul_f32_e32 v65, 0xbfb8aa3b, v52
	v_mul_f32_e32 v57, 0xbfb8aa3b, v53
	v_mul_f32_e32 v67, 0xbfb8aa3b, v54
	v_mul_f32_e32 v68, 0xbfb8aa3b, v55
	v_mul_f32_e32 v69, 0xbfb8aa3b, v48
	v_mul_f32_e32 v70, 0xbfb8aa3b, v49
	v_mul_f32_e32 v66, 0xbfb8aa3b, v50
	v_mul_f32_e32 v61, 0xbfb8aa3b, v51
	v_exp_f32_e32 v65, v65
	v_exp_f32_e32 v57, v57
	v_exp_f32_e32 v67, v67
	v_exp_f32_e32 v68, v68
	v_exp_f32_e32 v69, v69
	v_exp_f32_e32 v70, v70
	v_exp_f32_e32 v66, v66
	v_exp_f32_e32 v61, v61
	v_add_f32_e32 v65, 1.0, v65
	v_add_f32_e32 v57, 1.0, v57
	v_add_f32_e32 v67, 1.0, v67
	v_add_f32_e32 v68, 1.0, v68
	v_add_f32_e32 v69, 1.0, v69
	v_add_f32_e32 v70, 1.0, v70
	v_add_f32_e32 v66, 1.0, v66
	v_add_f32_e32 v61, 1.0, v61
	v_rcp_f32_e32 v65, v65
	v_rcp_f32_e32 v57, v57
	v_rcp_f32_e32 v67, v67
	v_rcp_f32_e32 v68, v68
	v_rcp_f32_e32 v69, v69
	v_rcp_f32_e32 v70, v70
	v_rcp_f32_e32 v66, v66
	v_rcp_f32_e32 v61, v61
	v_mul_f32_e32 v65, v52, v65
	v_mul_f32_e32 v57, v53, v57
	v_mul_f32_e32 v67, v54, v67
	v_mul_f32_e32 v68, v55, v68
	v_mul_f32_e32 v69, v48, v69
	v_mul_f32_e32 v70, v49, v70
	v_mul_f32_e32 v66, v50, v66
	v_mul_f32_e32 v61, v51, v61
	v_cvt_pk_bf16_f32 v58, v65, v57
	v_cvt_pk_bf16_f32 v59, v67, v68
	v_cvt_pk_bf16_f32 v60, v69, v70
	v_cvt_pk_bf16_f32 v61, v66, v61
	s_nop 1
	v_addc_co_u32_e32 v63, vcc, 0, v63, vcc
	flat_store_dwordx4 v[62:63], v[58:61] offset:1792 nt

; __device__ __forceinline__ unsigned pk_bf16(float lo, float hi) { const f32x2 v = {lo, hi}; return __builtin_bit_cast(unsigned, __builtin_convertvector(v, nbf16x2)); }
; __device__ __forceinline__ void st8_bf16(bf16_t* p, const f32x4 a, const f32x4 b) { __builtin_nontemporal_store((u32x4){pk_bf16(a[0], a[1]), pk_bf16(a[2], a[3]), pk_bf16(b[0], b[1]), pk_bf16(b[2], b[3])}, (u32x4*)p); }
; __device__ __forceinline__ void st8_f32(float* p, const f32x4 a, const f32x4 b) { __builtin_nontemporal_store(a, (f32x4*)p); __builtin_nontemporal_store(b, (f32x4*)(p + 4)); }
; __device__ __forceinline__ f32x4 silu4(const f32x4 v) { return (f32x4){v[0] / (1.f + __expf(-v[0])), v[1] / (1.f + __expf(-v[1])), v[2] / (1.f + __expf(-v[2])), v[3] / (1.f + __expf(-v[3]))}; }
;     __device__ __forceinline__ void store8(int row, int col, const f32x4 v, const f32x4 w) const {
;     ...
;         else if (col < RWIN) st8_bf16((bf16_t*)(ws + WS_GATE) + (size_t)row * BR + (col - RWP - 512), silu4(v), silu4(w));
.LBB0_291:
	s_or_b64 exec, exec, s[42:43]
	v_add_u32_e32 v48, 0xa0, v148
	s_and_saveexec_b64 s[10:11], s[8:9]
	s_xor_b64 s[10:11], exec, s[10:11]
	s_cbranch_execz .LBB0_298
	s_cmpk_gt_u32 s31, 0x147f
	s_mov_b64 s[42:43], -1
	s_cbranch_scc0 .LBB0_296
	s_cmpk_gt_u32 s31, 0x1c7f
	s_cbranch_scc1 .LBB0_295
	v_ashrrev_i32_e32 v49, 31, v48
	v_lshlrev_b64 v[52:53], 12, v[48:49]
	v_lshl_add_u64 v[52:53], s[40:41], 0, v[52:53]
	v_mov_b32_e32 v144, v146
	v_lshl_add_u64 v[54:55], v[144:145], 1, v[52:53]
	v_add_co_u32_e32 v54, vcc, 0x15add000, v54
	v_mul_f32_e32 v58, 0xbfb8aa3b, v44
	v_mul_f32_e32 v49, 0xbfb8aa3b, v45
	v_mul_f32_e32 v60, 0xbfb8aa3b, v46
	v_mul_f32_e32 v61, 0xbfb8aa3b, v47
	v_mul_f32_e32 v62, 0xbfb8aa3b, v40
	v_mul_f32_e32 v63, 0xbfb8aa3b, v41
	v_mul_f32_e32 v59, 0xbfb8aa3b, v42
	v_mul_f32_e32 v53, 0xbfb8aa3b, v43
	v_exp_f32_e32 v58, v58
	v_exp_f32_e32 v49, v49
	v_exp_f32_e32 v60, v60
	v_exp_f32_e32 v61, v61
	v_exp_f32_e32 v62, v62
	v_exp_f32_e32 v63, v63
	v_exp_f32_e32 v59, v59
	v_exp_f32_e32 v53, v53
	v_add_f32_e32 v58, 1.0, v58
	v_add_f32_e32 v49, 1.0, v49
	v_add_f32_e32 v60, 1.0, v60
	v_add_f32_e32 v61, 1.0, v61
	v_add_f32_e32 v62, 1.0, v62
	v_add_f32_e32 v63, 1.0, v63
	v_add_f32_e32 v59, 1.0, v59
	v_add_f32_e32 v53, 1.0, v53
	v_rcp_f32_e32 v58, v58
	v_rcp_f32_e32 v49, v49
	v_rcp_f32_e32 v60, v60
	v_rcp_f32_e32 v61, v61
	v_rcp_f32_e32 v62, v62
	v_rcp_f32_e32 v63, v63
	v_rcp_f32_e32 v59, v59
	v_rcp_f32_e32 v53, v53
	v_mul_f32_e32 v58, v44, v58
	v_mul_f32_e32 v49, v45, v49
	v_mul_f32_e32 v60, v46, v60
	v_mul_f32_e32 v61, v47, v61
	v_mul_f32_e32 v62, v40, v62
	v_mul_f32_e32 v63, v41, v63
	v_mul_f32_e32 v59, v42, v59
	v_mul_f32_e32 v53, v43, v53
	v_cvt_pk_bf16_f32 v50, v58, v49
	v_cvt_pk_bf16_f32 v51, v60, v61
	v_cvt_pk_bf16_f32 v52, v62, v63
	v_cvt_pk_bf16_f32 v53, v59, v53
	s_nop 1
	v_addc_co_u32_e32 v55, vcc, 0, v55, vcc
	flat_store_dwordx4 v[54:55], v[50:53] offset:1792 nt

; __device__ __forceinline__ unsigned pk_bf16(float lo, float hi) { const f32x2 v = {lo, hi}; return __builtin_bit_cast(unsigned, __builtin_convertvector(v, nbf16x2)); }
; __device__ __forceinline__ void st8_bf16(bf16_t* p, const f32x4 a, const f32x4 b) { __builtin_nontemporal_store((u32x4){pk_bf16(a[0], a[1]), pk_bf16(a[2], a[3]), pk_bf16(b[0], b[1]), pk_bf16(b[2], b[3])}, (u32x4*)p); }
; __device__ __forceinline__ void st8_f32(float* p, const f32x4 a, const f32x4 b) { __builtin_nontemporal_store(a, (f32x4*)p); __builtin_nontemporal_store(b, (f32x4*)(p + 4)); }
; __device__ __forceinline__ f32x4 silu4(const f32x4 v) { return (f32x4){v[0] / (1.f + __expf(-v[0])), v[1] / (1.f + __expf(-v[1])), v[2] / (1.f + __expf(-v[2])), v[3] / (1.f + __expf(-v[3]))}; }
;     __device__ __forceinline__ void store8(int row, int col, const f32x4 v, const f32x4 w) const {
;     ...
;         else if (col < RWIN) st8_bf16((bf16_t*)(ws + WS_GATE) + (size_t)row * BR + (col - RWP - 512), silu4(v), silu4(w));
.LBB0_300:
	s_or_b64 exec, exec, s[10:11]
	v_add_u32_e32 v40, 0xb0, v148
	s_and_saveexec_b64 s[10:11], s[8:9]
	s_xor_b64 s[8:9], exec, s[10:11]
	s_cbranch_execz .LBB0_307
	s_cmpk_gt_u32 s31, 0x147f
	s_mov_b64 s[10:11], -1
	s_cbranch_scc0 .LBB0_305
	s_cmpk_gt_u32 s31, 0x1c7f
	s_cbranch_scc1 .LBB0_304
	v_ashrrev_i32_e32 v41, 31, v40
	v_lshlrev_b64 v[44:45], 12, v[40:41]
	v_lshl_add_u64 v[44:45], s[40:41], 0, v[44:45]
	v_mov_b32_e32 v144, v146
	v_lshl_add_u64 v[46:47], v[144:145], 1, v[44:45]
	v_add_co_u32_e32 v46, vcc, 0x15add000, v46
	v_mul_f32_e32 v49, 0xbfb8aa3b, v36
	v_mul_f32_e32 v41, 0xbfb8aa3b, v37
	v_mul_f32_e32 v51, 0xbfb8aa3b, v38
	v_mul_f32_e32 v52, 0xbfb8aa3b, v39
	v_mul_f32_e32 v53, 0xbfb8aa3b, v32
	v_mul_f32_e32 v54, 0xbfb8aa3b, v33
	v_mul_f32_e32 v50, 0xbfb8aa3b, v34
	v_mul_f32_e32 v45, 0xbfb8aa3b, v35
	v_exp_f32_e32 v49, v49
	v_exp_f32_e32 v41, v41
	v_exp_f32_e32 v51, v51
	v_exp_f32_e32 v52, v52
	v_exp_f32_e32 v53, v53
	v_exp_f32_e32 v54, v54
	v_exp_f32_e32 v50, v50
	v_exp_f32_e32 v45, v45
	v_add_f32_e32 v49, 1.0, v49
	v_add_f32_e32 v41, 1.0, v41
	v_add_f32_e32 v51, 1.0, v51
	v_add_f32_e32 v52, 1.0, v52
	v_add_f32_e32 v53, 1.0, v53
	v_add_f32_e32 v54, 1.0, v54
	v_add_f32_e32 v50, 1.0, v50
	v_add_f32_e32 v45, 1.0, v45
	v_rcp_f32_e32 v49, v49
	v_rcp_f32_e32 v41, v41
	v_rcp_f32_e32 v51, v51
	v_rcp_f32_e32 v52, v52
	v_rcp_f32_e32 v53, v53
	v_rcp_f32_e32 v54, v54
	v_rcp_f32_e32 v50, v50
	v_rcp_f32_e32 v45, v45
	v_mul_f32_e32 v49, v36, v49
	v_mul_f32_e32 v41, v37, v41
	v_mul_f32_e32 v51, v38, v51
	v_mul_f32_e32 v52, v39, v52
	v_mul_f32_e32 v53, v32, v53
	v_mul_f32_e32 v54, v33, v54
	v_mul_f32_e32 v50, v34, v50
	v_mul_f32_e32 v45, v35, v45
	v_cvt_pk_bf16_f32 v42, v49, v41
	v_cvt_pk_bf16_f32 v43, v51, v52
	v_cvt_pk_bf16_f32 v44, v53, v54
	v_cvt_pk_bf16_f32 v45, v50, v45
	s_nop 1
	v_addc_co_u32_e32 v47, vcc, 0, v47, vcc
	flat_store_dwordx4 v[46:47], v[42:45] offset:1792 nt

; __device__ __forceinline__ unsigned pk_bf16(float lo, float hi) { const f32x2 v = {lo, hi}; return __builtin_bit_cast(unsigned, __builtin_convertvector(v, nbf16x2)); }
; __device__ __forceinline__ void st8_bf16(bf16_t* p, const f32x4 a, const f32x4 b) { __builtin_nontemporal_store((u32x4){pk_bf16(a[0], a[1]), pk_bf16(a[2], a[3]), pk_bf16(b[0], b[1]), pk_bf16(b[2], b[3])}, (u32x4*)p); }
; __device__ __forceinline__ void st8_f32(float* p, const f32x4 a, const f32x4 b) { __builtin_nontemporal_store(a, (f32x4*)p); __builtin_nontemporal_store(b, (f32x4*)(p + 4)); }
; __device__ __forceinline__ f32x4 silu4(const f32x4 v) { return (f32x4){v[0] / (1.f + __expf(-v[0])), v[1] / (1.f + __expf(-v[1])), v[2] / (1.f + __expf(-v[2])), v[3] / (1.f + __expf(-v[3]))}; }
;     __device__ __forceinline__ void store8(int row, int col, const f32x4 v, const f32x4 w) const {
;     ...
;         else if (col < RWIN) st8_bf16((bf16_t*)(ws + WS_GATE) + (size_t)row * BR + (col - RWP - 512), silu4(v), silu4(w));
.LBB0_326:
	v_cmp_lt_u32_e32 vcc, s62, v96
	s_and_saveexec_b64 s[10:11], vcc
	s_xor_b64 s[10:11], exec, s[10:11]
	s_cbranch_execz .LBB0_330
	v_cmp_gt_u32_e32 vcc, s66, v96
	s_and_saveexec_b64 s[42:43], vcc
	s_cbranch_execz .LBB0_329
	v_ashrrev_i32_e32 v65, 31, v64
	v_lshlrev_b64 v[34:35], 12, v[64:65]
	v_lshl_add_u64 v[34:35], s[40:41], 0, v[34:35]
	v_mov_b32_e32 v144, v146
	v_lshl_add_u64 v[36:37], v[144:145], 1, v[34:35]
	v_add_co_u32_e32 v36, vcc, 0x15add000, v36
	v_mul_f32_e32 v41, 0xbfb8aa3b, v28
	v_mul_f32_e32 v39, 0xbfb8aa3b, v29
	v_mul_f32_e32 v42, 0xbfb8aa3b, v30
	v_mul_f32_e32 v43, 0xbfb8aa3b, v31
	v_mul_f32_e32 v44, 0xbfb8aa3b, v24
	v_mul_f32_e32 v45, 0xbfb8aa3b, v25
	v_mul_f32_e32 v38, 0xbfb8aa3b, v26
	v_mul_f32_e32 v35, 0xbfb8aa3b, v27
	v_exp_f32_e32 v41, v41
	v_exp_f32_e32 v39, v39
	v_exp_f32_e32 v42, v42
	v_exp_f32_e32 v43, v43
	v_exp_f32_e32 v44, v44
	v_exp_f32_e32 v45, v45
	v_exp_f32_e32 v38, v38
	v_exp_f32_e32 v35, v35
	v_add_f32_e32 v41, 1.0, v41
	v_add_f32_e32 v39, 1.0, v39
	v_add_f32_e32 v42, 1.0, v42
	v_add_f32_e32 v43, 1.0, v43
	v_add_f32_e32 v44, 1.0, v44
	v_add_f32_e32 v45, 1.0, v45
	v_add_f32_e32 v38, 1.0, v38
	v_add_f32_e32 v35, 1.0, v35
	v_rcp_f32_e32 v41, v41
	v_rcp_f32_e32 v39, v39
	v_rcp_f32_e32 v42, v42
	v_rcp_f32_e32 v43, v43
	v_rcp_f32_e32 v44, v44
	v_rcp_f32_e32 v45, v45
	v_rcp_f32_e32 v38, v38
	v_rcp_f32_e32 v35, v35
	v_mul_f32_e32 v41, v28, v41
	v_mul_f32_e32 v39, v29, v39
	v_mul_f32_e32 v42, v30, v42
	v_mul_f32_e32 v43, v31, v43
	v_mul_f32_e32 v44, v24, v44
	v_mul_f32_e32 v45, v25, v45
	v_mul_f32_e32 v38, v26, v38
	v_mul_f32_e32 v35, v27, v35
	v_cvt_pk_bf16_f32 v32, v41, v39
	v_cvt_pk_bf16_f32 v33, v42, v43
	v_cvt_pk_bf16_f32 v34, v44, v45
	v_cvt_pk_bf16_f32 v35, v38, v35
	s_nop 1
	v_addc_co_u32_e32 v37, vcc, 0, v37, vcc
	flat_store_dwordx4 v[36:37], v[32:35] offset:2048 nt

; __device__ __forceinline__ unsigned pk_bf16(float lo, float hi) { const f32x2 v = {lo, hi}; return __builtin_bit_cast(unsigned, __builtin_convertvector(v, nbf16x2)); }
; __device__ __forceinline__ void st8_bf16(bf16_t* p, const f32x4 a, const f32x4 b) { __builtin_nontemporal_store((u32x4){pk_bf16(a[0], a[1]), pk_bf16(a[2], a[3]), pk_bf16(b[0], b[1]), pk_bf16(b[2], b[3])}, (u32x4*)p); }
; __device__ __forceinline__ void st8_f32(float* p, const f32x4 a, const f32x4 b) { __builtin_nontemporal_store(a, (f32x4*)p); __builtin_nontemporal_store(b, (f32x4*)(p + 4)); }
; __device__ __forceinline__ f32x4 silu4(const f32x4 v) { return (f32x4){v[0] / (1.f + __expf(-v[0])), v[1] / (1.f + __expf(-v[1])), v[2] / (1.f + __expf(-v[2])), v[3] / (1.f + __expf(-v[3]))}; }
;     __device__ __forceinline__ void store8(int row, int col, const f32x4 v, const f32x4 w) const {
;     ...
;         else if (col < RWIN) st8_bf16((bf16_t*)(ws + WS_GATE) + (size_t)row * BR + (col - RWP - 512), silu4(v), silu4(w));
.LBB0_334:
	v_cmp_lt_u32_e32 vcc, s62, v96
	s_and_saveexec_b64 s[10:11], vcc
	s_xor_b64 s[10:11], exec, s[10:11]
	s_cbranch_execz .LBB0_338
	v_cmp_gt_u32_e32 vcc, s66, v96
	s_and_saveexec_b64 s[42:43], vcc
	s_cbranch_execz .LBB0_337
	v_ashrrev_i32_e32 v57, 31, v56
	v_lshlrev_b64 v[26:27], 12, v[56:57]
	v_lshl_add_u64 v[26:27], s[40:41], 0, v[26:27]
	v_mov_b32_e32 v144, v146
	v_lshl_add_u64 v[28:29], v[144:145], 1, v[26:27]
	v_add_co_u32_e32 v28, vcc, 0x15add000, v28
	v_mul_f32_e32 v32, 0xbfb8aa3b, v20
	v_mul_f32_e32 v31, 0xbfb8aa3b, v21
	v_mul_f32_e32 v33, 0xbfb8aa3b, v22
	v_mul_f32_e32 v34, 0xbfb8aa3b, v23
	v_mul_f32_e32 v35, 0xbfb8aa3b, v16
	v_mul_f32_e32 v36, 0xbfb8aa3b, v17
	v_mul_f32_e32 v30, 0xbfb8aa3b, v18
	v_mul_f32_e32 v27, 0xbfb8aa3b, v19
	v_exp_f32_e32 v32, v32
	v_exp_f32_e32 v31, v31
	v_exp_f32_e32 v33, v33
	v_exp_f32_e32 v34, v34
	v_exp_f32_e32 v35, v35
	v_exp_f32_e32 v36, v36
	v_exp_f32_e32 v30, v30
	v_exp_f32_e32 v27, v27
	v_add_f32_e32 v32, 1.0, v32
	v_add_f32_e32 v31, 1.0, v31
	v_add_f32_e32 v33, 1.0, v33
	v_add_f32_e32 v34, 1.0, v34
	v_add_f32_e32 v35, 1.0, v35
	v_add_f32_e32 v36, 1.0, v36
	v_add_f32_e32 v30, 1.0, v30
	v_add_f32_e32 v27, 1.0, v27
	v_rcp_f32_e32 v32, v32
	v_rcp_f32_e32 v31, v31
	v_rcp_f32_e32 v33, v33
	v_rcp_f32_e32 v34, v34
	v_rcp_f32_e32 v35, v35
	v_rcp_f32_e32 v36, v36
	v_rcp_f32_e32 v30, v30
	v_rcp_f32_e32 v27, v27
	v_mul_f32_e32 v32, v20, v32
	v_mul_f32_e32 v31, v21, v31
	v_mul_f32_e32 v33, v22, v33
	v_mul_f32_e32 v34, v23, v34
	v_mul_f32_e32 v35, v16, v35
	v_mul_f32_e32 v36, v17, v36
	v_mul_f32_e32 v30, v18, v30
	v_mul_f32_e32 v27, v19, v27
	v_cvt_pk_bf16_f32 v24, v32, v31
	v_cvt_pk_bf16_f32 v25, v33, v34
	v_cvt_pk_bf16_f32 v26, v35, v36
	v_cvt_pk_bf16_f32 v27, v30, v27
	s_nop 1
	v_addc_co_u32_e32 v29, vcc, 0, v29, vcc
	flat_store_dwordx4 v[28:29], v[24:27] offset:2048 nt

; __device__ __forceinline__ unsigned pk_bf16(float lo, float hi) { const f32x2 v = {lo, hi}; return __builtin_bit_cast(unsigned, __builtin_convertvector(v, nbf16x2)); }
; __device__ __forceinline__ void st8_bf16(bf16_t* p, const f32x4 a, const f32x4 b) { __builtin_nontemporal_store((u32x4){pk_bf16(a[0], a[1]), pk_bf16(a[2], a[3]), pk_bf16(b[0], b[1]), pk_bf16(b[2], b[3])}, (u32x4*)p); }
; __device__ __forceinline__ void st8_f32(float* p, const f32x4 a, const f32x4 b) { __builtin_nontemporal_store(a, (f32x4*)p); __builtin_nontemporal_store(b, (f32x4*)(p + 4)); }
; __device__ __forceinline__ f32x4 silu4(const f32x4 v) { return (f32x4){v[0] / (1.f + __expf(-v[0])), v[1] / (1.f + __expf(-v[1])), v[2] / (1.f + __expf(-v[2])), v[3] / (1.f + __expf(-v[3]))}; }
;     __device__ __forceinline__ void store8(int row, int col, const f32x4 v, const f32x4 w) const {
;     ...
;         else if (col < RWIN) st8_bf16((bf16_t*)(ws + WS_GATE) + (size_t)row * BR + (col - RWP - 512), silu4(v), silu4(w));
.LBB0_344:
	v_cmp_lt_u32_e32 vcc, s62, v96
	s_and_saveexec_b64 s[10:11], vcc
	s_xor_b64 s[10:11], exec, s[10:11]
	s_cbranch_execz .LBB0_348
	v_cmp_gt_u32_e32 vcc, s66, v96
	s_and_saveexec_b64 s[42:43], vcc
	s_cbranch_execz .LBB0_347
	v_ashrrev_i32_e32 v49, 31, v48
	v_lshlrev_b64 v[18:19], 12, v[48:49]
	v_lshl_add_u64 v[18:19], s[40:41], 0, v[18:19]
	v_mov_b32_e32 v144, v146
	v_lshl_add_u64 v[20:21], v[144:145], 1, v[18:19]
	v_add_co_u32_e32 v20, vcc, 0x15add000, v20
	v_mul_f32_e32 v24, 0xbfb8aa3b, v12
	v_mul_f32_e32 v23, 0xbfb8aa3b, v13
	v_mul_f32_e32 v25, 0xbfb8aa3b, v14
	v_mul_f32_e32 v26, 0xbfb8aa3b, v15
	v_mul_f32_e32 v27, 0xbfb8aa3b, v8
	v_mul_f32_e32 v28, 0xbfb8aa3b, v9
	v_mul_f32_e32 v22, 0xbfb8aa3b, v10
	v_mul_f32_e32 v19, 0xbfb8aa3b, v11
	v_exp_f32_e32 v24, v24
	v_exp_f32_e32 v23, v23
	v_exp_f32_e32 v25, v25
	v_exp_f32_e32 v26, v26
	v_exp_f32_e32 v27, v27
	v_exp_f32_e32 v28, v28
	v_exp_f32_e32 v22, v22
	v_exp_f32_e32 v19, v19
	v_add_f32_e32 v24, 1.0, v24
	v_add_f32_e32 v23, 1.0, v23
	v_add_f32_e32 v25, 1.0, v25
	v_add_f32_e32 v26, 1.0, v26
	v_add_f32_e32 v27, 1.0, v27
	v_add_f32_e32 v28, 1.0, v28
	v_add_f32_e32 v22, 1.0, v22
	v_add_f32_e32 v19, 1.0, v19
	v_rcp_f32_e32 v24, v24
	v_rcp_f32_e32 v23, v23
	v_rcp_f32_e32 v25, v25
	v_rcp_f32_e32 v26, v26
	v_rcp_f32_e32 v27, v27
	v_rcp_f32_e32 v28, v28
	v_rcp_f32_e32 v22, v22
	v_rcp_f32_e32 v19, v19
	v_mul_f32_e32 v24, v12, v24
	v_mul_f32_e32 v23, v13, v23
	v_mul_f32_e32 v25, v14, v25
	v_mul_f32_e32 v26, v15, v26
	v_mul_f32_e32 v27, v8, v27
	v_mul_f32_e32 v28, v9, v28
	v_mul_f32_e32 v22, v10, v22
	v_mul_f32_e32 v19, v11, v19
	v_cvt_pk_bf16_f32 v16, v24, v23
	v_cvt_pk_bf16_f32 v17, v25, v26
	v_cvt_pk_bf16_f32 v18, v27, v28
	v_cvt_pk_bf16_f32 v19, v22, v19
	s_nop 1
	v_addc_co_u32_e32 v21, vcc, 0, v21, vcc
	flat_store_dwordx4 v[20:21], v[16:19] offset:2048 nt

; __device__ __forceinline__ unsigned pk_bf16(float lo, float hi) { const f32x2 v = {lo, hi}; return __builtin_bit_cast(unsigned, __builtin_convertvector(v, nbf16x2)); }
; __device__ __forceinline__ void st8_bf16(bf16_t* p, const f32x4 a, const f32x4 b) { __builtin_nontemporal_store((u32x4){pk_bf16(a[0], a[1]), pk_bf16(a[2], a[3]), pk_bf16(b[0], b[1]), pk_bf16(b[2], b[3])}, (u32x4*)p); }
; __device__ __forceinline__ void st8_f32(float* p, const f32x4 a, const f32x4 b) { __builtin_nontemporal_store(a, (f32x4*)p); __builtin_nontemporal_store(b, (f32x4*)(p + 4)); }
; __device__ __forceinline__ f32x4 silu4(const f32x4 v) { return (f32x4){v[0] / (1.f + __expf(-v[0])), v[1] / (1.f + __expf(-v[1])), v[2] / (1.f + __expf(-v[2])), v[3] / (1.f + __expf(-v[3]))}; }
;     __device__ __forceinline__ void store8(int row, int col, const f32x4 v, const f32x4 w) const {
;     ...
;         else if (col < RWIN) st8_bf16((bf16_t*)(ws + WS_GATE) + (size_t)row * BR + (col - RWP - 512), silu4(v), silu4(w));
.LBB0_352:
	v_cmp_lt_u32_e32 vcc, s62, v96
	s_and_saveexec_b64 s[8:9], vcc
	s_xor_b64 s[8:9], exec, s[8:9]
	s_cbranch_execz .LBB0_356
	v_cmp_gt_u32_e32 vcc, s66, v96
	s_and_saveexec_b64 s[10:11], vcc
	s_cbranch_execz .LBB0_355
	v_ashrrev_i32_e32 v41, 31, v40
	v_lshlrev_b64 v[10:11], 12, v[40:41]
	v_lshl_add_u64 v[10:11], s[40:41], 0, v[10:11]
	v_mov_b32_e32 v147, v145
	v_lshl_add_u64 v[12:13], v[146:147], 1, v[10:11]
	v_add_co_u32_e32 v12, vcc, 0x15add000, v12
	v_mul_f32_e32 v16, 0xbfb8aa3b, v4
	v_mul_f32_e32 v15, 0xbfb8aa3b, v5
	v_mul_f32_e32 v17, 0xbfb8aa3b, v6
	v_mul_f32_e32 v18, 0xbfb8aa3b, v7
	v_mul_f32_e32 v19, 0xbfb8aa3b, v0
	v_mul_f32_e32 v20, 0xbfb8aa3b, v1
	v_mul_f32_e32 v14, 0xbfb8aa3b, v2
	v_mul_f32_e32 v11, 0xbfb8aa3b, v3
	v_exp_f32_e32 v16, v16
	v_exp_f32_e32 v15, v15
	v_exp_f32_e32 v17, v17
	v_exp_f32_e32 v18, v18
	v_exp_f32_e32 v19, v19
	v_exp_f32_e32 v20, v20
	v_exp_f32_e32 v14, v14
	v_exp_f32_e32 v11, v11
	v_add_f32_e32 v16, 1.0, v16
	v_add_f32_e32 v15, 1.0, v15
	v_add_f32_e32 v17, 1.0, v17
	v_add_f32_e32 v18, 1.0, v18
	v_add_f32_e32 v19, 1.0, v19
	v_add_f32_e32 v20, 1.0, v20
	v_add_f32_e32 v14, 1.0, v14
	v_add_f32_e32 v11, 1.0, v11
	v_rcp_f32_e32 v16, v16
	v_rcp_f32_e32 v15, v15
	v_rcp_f32_e32 v17, v17
	v_rcp_f32_e32 v18, v18
	v_rcp_f32_e32 v19, v19
	v_rcp_f32_e32 v20, v20
	v_rcp_f32_e32 v14, v14
	v_rcp_f32_e32 v11, v11
	v_mul_f32_e32 v16, v4, v16
	v_mul_f32_e32 v15, v5, v15
	v_mul_f32_e32 v17, v6, v17
	v_mul_f32_e32 v18, v7, v18
	v_mul_f32_e32 v19, v0, v19
	v_mul_f32_e32 v20, v1, v20
	v_mul_f32_e32 v14, v2, v14
	v_mul_f32_e32 v11, v3, v11
	v_cvt_pk_bf16_f32 v8, v16, v15
	v_cvt_pk_bf16_f32 v9, v17, v18
	v_cvt_pk_bf16_f32 v10, v19, v20
	v_cvt_pk_bf16_f32 v11, v14, v11
	s_nop 1
	v_addc_co_u32_e32 v13, vcc, 0, v13, vcc
	flat_store_dwordx4 v[12:13], v[8:11] offset:2048 nt

; #define SB __builtin_amdgcn_sched_barrier(0)
; #define CMP(G, c8) { CMP1(G, 0, 2 * (c8)) CMP1(G, 1, 2 * (c8) + 1) }
; __device__ __forceinline__ void phase_scan(const Args& a, unsigned char* lds) {
;     ...
;                     for (int s = 0; s < 16; ++s) {
;                         const float* vs = vb + s * 384;
;                         const float vi = vs[128 - cb + srow];
;                         f32x4 G0[8], G1[8], G2[8];
;                         LDG(G0, 0) SB;
;                         LDG(G1, 1) SB;
;                         f32x2 c0 = {0.f, 0.f}, c1 = {0.f, 0.f};
; #pragma unroll
;                         for (int j = 0; j < 8; ++j) { c0 += S2[2 * j] * (f32x2){KA[j][0], KA[j][1]}; c1 += S2[2 * j + 1] * (f32x2){KA[j][2], KA[j][3]}; }
;                         float cs = (c0.x + c0.y) + (c1.x + c1.y);
;                         cs += dpp_f(cs, 0);
;                         const float sa = -cs;
;                         const f32x2 sa2 = {sa, sa}, v2 = {vi, vi};
;                         f32x2 y0 = {0.f, 0.f}, y1 = {0.f, 0.f};
;                         SB; LDG(G2, 2) SB; CMP(G0, 0) SB;
;                         LDG(G0, 3) SB; CMP(G1, 1) SB;
;                         CMP(G2, 2) SB;
; #pragma unroll
;                         for (int j = 0; j < 8; ++j) KA[j] = *(const f32x4*)(vs + 384 + 256 + 4 * j);
;                         SB; CMP(G0, 3) SB;
;                         float ys = (y0.x + y0.y) + (y1.x + y1.y);
;                         ys += dpp_f(ys, 0);
;                         if ((lane & 1) == 0) yb[s * 64 + srow] = ys;
.Lscan_step:
	s_waitcnt lgkmcnt(13)
	v_pk_mul_f32 v[196:197], v[0:1], v[32:33]
	v_pk_mul_f32 v[200:201], v[16:17], v[32:33]
	v_pk_mul_f32 v[204:205], v[0:1], v[48:49]
	v_pk_mul_f32 v[208:209], v[16:17], v[48:49]
	v_pk_fma_f32 v[196:197], v[2:3], v[34:35], v[196:197]
	v_pk_fma_f32 v[200:201], v[18:19], v[34:35], v[200:201]
	v_pk_fma_f32 v[204:205], v[2:3], v[50:51], v[204:205]
	v_pk_fma_f32 v[208:209], v[18:19], v[50:51], v[208:209]
	ds_read_b128 v[32:35], v232 offset:2560
	ds_read_b128 v[48:51], v232 offset:0
	v_pk_fma_f32 v[196:197], v[4:5], v[36:37], v[196:197]
	v_pk_fma_f32 v[200:201], v[20:21], v[36:37], v[200:201]
	v_pk_fma_f32 v[204:205], v[4:5], v[52:53], v[204:205]
	v_pk_fma_f32 v[208:209], v[20:21], v[52:53], v[208:209]
	v_pk_fma_f32 v[196:197], v[6:7], v[38:39], v[196:197]
	v_pk_fma_f32 v[200:201], v[22:23], v[38:39], v[200:201]
	v_pk_fma_f32 v[204:205], v[6:7], v[54:55], v[204:205]
	v_pk_fma_f32 v[208:209], v[22:23], v[54:55], v[208:209]
	ds_read_b128 v[36:39], v232 offset:2576
	ds_read_b128 v[52:55], v232 offset:16
	v_pk_fma_f32 v[196:197], v[8:9], v[40:41], v[196:197]
	v_pk_fma_f32 v[200:201], v[24:25], v[40:41], v[200:201]
	v_pk_fma_f32 v[204:205], v[8:9], v[56:57], v[204:205]
	v_pk_fma_f32 v[208:209], v[24:25], v[56:57], v[208:209]
	v_pk_fma_f32 v[196:197], v[10:11], v[42:43], v[196:197]
	v_pk_fma_f32 v[200:201], v[26:27], v[42:43], v[200:201]
	v_pk_fma_f32 v[204:205], v[10:11], v[58:59], v[204:205]
	v_pk_fma_f32 v[208:209], v[26:27], v[58:59], v[208:209]
	ds_read_b128 v[40:43], v232 offset:2592
	ds_read_b128 v[56:59], v232 offset:32
	v_pk_fma_f32 v[196:197], v[12:13], v[44:45], v[196:197]
	v_pk_fma_f32 v[200:201], v[28:29], v[44:45], v[200:201]
	v_pk_fma_f32 v[204:205], v[12:13], v[60:61], v[204:205]
	v_pk_fma_f32 v[208:209], v[28:29], v[60:61], v[208:209]
	v_pk_fma_f32 v[196:197], v[14:15], v[46:47], v[196:197]
	v_pk_fma_f32 v[200:201], v[30:31], v[46:47], v[200:201]
	v_pk_fma_f32 v[204:205], v[14:15], v[62:63], v[204:205]
	v_pk_fma_f32 v[208:209], v[30:31], v[62:63], v[208:209]
	ds_read_b128 v[44:47], v232 offset:2608
	ds_read_b128 v[60:63], v232 offset:48
	v_add_f32_e32 v212, v196, v197
	v_add_f32_e32 v213, v200, v201
	v_add_f32_e32 v214, v204, v205
	v_add_f32_e32 v215, v208, v209
	v_add_f32_dpp v212, v212, v212 quad_perm:[1,0,3,2] row_mask:0xf bank_mask:0xf
	v_add_f32_dpp v213, v213, v213 quad_perm:[1,0,3,2] row_mask:0xf bank_mask:0xf
	v_add_f32_dpp v214, v214, v214 quad_perm:[1,0,3,2] row_mask:0xf bank_mask:0xf
	v_add_f32_dpp v215, v215, v215 quad_perm:[1,0,3,2] row_mask:0xf bank_mask:0xf
	v_add_f32_dpp v212, v212, v212 quad_perm:[2,3,0,1] row_mask:0xf bank_mask:0xf
	v_add_f32_dpp v213, v213, v213 quad_perm:[2,3,0,1] row_mask:0xf bank_mask:0xf
	v_add_f32_dpp v214, v214, v214 quad_perm:[2,3,0,1] row_mask:0xf bank_mask:0xf
	v_add_f32_dpp v215, v215, v215 quad_perm:[2,3,0,1] row_mask:0xf bank_mask:0xf
	s_cmp_eq_u32 s58, 0
	s_cbranch_scc1 .Lscan_noy
	ds_write_b64 v234, v[214:215]
; #define SB __builtin_amdgcn_sched_barrier(0)
; #define CMP(G, c8) { CMP1(G, 0, 2 * (c8)) CMP1(G, 1, 2 * (c8) + 1) }
; __device__ __forceinline__ void phase_scan(const Args& a, unsigned char* lds) {
;     ...
;                     f32x4 KA[8];
; #pragma unroll
;                     for (int j = 0; j < 8; ++j) KA[j] = *(const f32x4*)(vb + 256 + 4 * j);
; #pragma nounroll
;                     for (int s = 0; s < 16; ++s) {
;                         const float* vs = vb + s * 384;
;                         const float vi = vs[128 - cb + srow];
;                         f32x4 G0[8], G1[8], G2[8];
;                         LDG(G0, 0) SB;
;                         LDG(G1, 1) SB;
;                         f32x2 c0 = {0.f, 0.f}, c1 = {0.f, 0.f};
; #pragma unroll
;                         for (int j = 0; j < 8; ++j) { c0 += S2[2 * j] * (f32x2){KA[j][0], KA[j][1]}; c1 += S2[2 * j + 1] * (f32x2){KA[j][2], KA[j][3]}; }
;                         float cs = (c0.x + c0.y) + (c1.x + c1.y);
;                         cs += dpp_f(cs, 0);
;                         const float sa = -cs;
;                         const f32x2 sa2 = {sa, sa}, v2 = {vi, vi};
;                         f32x2 y0 = {0.f, 0.f}, y1 = {0.f, 0.f};
;                         SB; LDG(G2, 2) SB; CMP(G0, 0) SB;
;                         LDG(G0, 3) SB; CMP(G1, 1) SB;
;                         CMP(G2, 2) SB;
; #pragma unroll
;                         for (int j = 0; j < 8; ++j) KA[j] = *(const f32x4*)(vs + 384 + 256 + 4 * j);
;                         SB; CMP(G0, 3) SB;
;                         float ys = (y0.x + y0.y) + (y1.x + y1.y);
;                         ys += dpp_f(ys, 0);
;                         if ((lane & 1) == 0) yb[s * 64 + srow] = ys;
.Lscan_noy:
	s_waitcnt lgkmcnt(8)
	v_mov_b64_e32 v[120:121], v[122:123]
	ds_read_b64 v[122:123], v233 offset:2048
	v_pk_mul_f32 v[216:217], v[88:89], v[212:213] op_sel_hi:[1,0] neg_lo:[0,1] neg_hi:[0,1]
	v_pk_mul_f32 v[218:219], v[90:91], v[212:213] op_sel_hi:[1,0] neg_lo:[0,1] neg_hi:[0,1]
	v_pk_mul_f32 v[220:221], v[88:89], v[212:213] op_sel:[0,1] op_sel_hi:[1,1] neg_lo:[0,1] neg_hi:[0,1]
	v_pk_mul_f32 v[222:223], v[90:91], v[212:213] op_sel:[0,1] op_sel_hi:[1,1] neg_lo:[0,1] neg_hi:[0,1]
	v_pk_fma_f32 v[216:217], v[104:105], v[120:121], v[216:217] op_sel_hi:[1,0,1]
	v_pk_fma_f32 v[218:219], v[106:107], v[120:121], v[218:219] op_sel_hi:[1,0,1]
	v_pk_fma_f32 v[220:221], v[104:105], v[120:121], v[220:221] op_sel:[0,1,0] op_sel_hi:[1,1,1]
	v_pk_fma_f32 v[222:223], v[106:107], v[120:121], v[222:223] op_sel:[0,1,0] op_sel_hi:[1,1,1]
	v_pk_fma_f32 v[0:1], v[0:1], v[180:181], v[216:217]
	v_pk_fma_f32 v[2:3], v[2:3], v[182:183], v[218:219]
	v_pk_fma_f32 v[16:17], v[16:17], v[180:181], v[220:221]
	v_pk_fma_f32 v[18:19], v[18:19], v[182:183], v[222:223]
	ds_read_b128 v[88:91], v232 offset:2816
	ds_read_b128 v[104:107], v232 offset:1792
	ds_read_b128 v[180:183], v232 offset:2304
	v_pk_mul_f32 v[224:225], v[92:93], v[212:213] op_sel_hi:[1,0] neg_lo:[0,1] neg_hi:[0,1]
	v_pk_mul_f32 v[226:227], v[94:95], v[212:213] op_sel_hi:[1,0] neg_lo:[0,1] neg_hi:[0,1]
	v_pk_mul_f32 v[228:229], v[92:93], v[212:213] op_sel:[0,1] op_sel_hi:[1,1] neg_lo:[0,1] neg_hi:[0,1]
	v_pk_mul_f32 v[230:231], v[94:95], v[212:213] op_sel:[0,1] op_sel_hi:[1,1] neg_lo:[0,1] neg_hi:[0,1]
	v_pk_fma_f32 v[224:225], v[108:109], v[120:121], v[224:225] op_sel_hi:[1,0,1]
	v_pk_fma_f32 v[226:227], v[110:111], v[120:121], v[226:227] op_sel_hi:[1,0,1]
	v_pk_fma_f32 v[228:229], v[108:109], v[120:121], v[228:229] op_sel:[0,1,0] op_sel_hi:[1,1,1]
	v_pk_fma_f32 v[230:231], v[110:111], v[120:121], v[230:231] op_sel:[0,1,0] op_sel_hi:[1,1,1]
	v_pk_fma_f32 v[4:5], v[4:5], v[184:185], v[224:225]
	v_pk_fma_f32 v[6:7], v[6:7], v[186:187], v[226:227]
	v_pk_fma_f32 v[20:21], v[20:21], v[184:185], v[228:229]
	v_pk_fma_f32 v[22:23], v[22:23], v[186:187], v[230:231]
	ds_read_b128 v[92:95], v232 offset:2832
	ds_read_b128 v[108:111], v232 offset:1808
	ds_read_b128 v[184:187], v232 offset:2320
	v_pk_mul_f32 v[216:217], v[96:97], v[212:213] op_sel_hi:[1,0] neg_lo:[0,1] neg_hi:[0,1]
	v_pk_mul_f32 v[218:219], v[98:99], v[212:213] op_sel_hi:[1,0] neg_lo:[0,1] neg_hi:[0,1]
	v_pk_mul_f32 v[220:221], v[96:97], v[212:213] op_sel:[0,1] op_sel_hi:[1,1] neg_lo:[0,1] neg_hi:[0,1]
	v_pk_mul_f32 v[222:223], v[98:99], v[212:213] op_sel:[0,1] op_sel_hi:[1,1] neg_lo:[0,1] neg_hi:[0,1]
	v_pk_fma_f32 v[216:217], v[112:113], v[120:121], v[216:217] op_sel_hi:[1,0,1]
	v_pk_fma_f32 v[218:219], v[114:115], v[120:121], v[218:219] op_sel_hi:[1,0,1]
	v_pk_fma_f32 v[220:221], v[112:113], v[120:121], v[220:221] op_sel:[0,1,0] op_sel_hi:[1,1,1]
	v_pk_fma_f32 v[222:223], v[114:115], v[120:121], v[222:223] op_sel:[0,1,0] op_sel_hi:[1,1,1]
	v_pk_fma_f32 v[8:9], v[8:9], v[188:189], v[216:217]
	v_pk_fma_f32 v[10:11], v[10:11], v[190:191], v[218:219]
	v_pk_fma_f32 v[24:25], v[24:25], v[188:189], v[220:221]
	v_pk_fma_f32 v[26:27], v[26:27], v[190:191], v[222:223]
	ds_read_b128 v[96:99], v232 offset:2848
	ds_read_b128 v[112:115], v232 offset:1824
	ds_read_b128 v[188:191], v232 offset:2336
	v_pk_mul_f32 v[224:225], v[100:101], v[212:213] op_sel_hi:[1,0] neg_lo:[0,1] neg_hi:[0,1]
	v_pk_mul_f32 v[226:227], v[102:103], v[212:213] op_sel_hi:[1,0] neg_lo:[0,1] neg_hi:[0,1]
	v_pk_mul_f32 v[228:229], v[100:101], v[212:213] op_sel:[0,1] op_sel_hi:[1,1] neg_lo:[0,1] neg_hi:[0,1]
	v_pk_mul_f32 v[230:231], v[102:103], v[212:213] op_sel:[0,1] op_sel_hi:[1,1] neg_lo:[0,1] neg_hi:[0,1]
	v_pk_fma_f32 v[224:225], v[116:117], v[120:121], v[224:225] op_sel_hi:[1,0,1]
	v_pk_fma_f32 v[226:227], v[118:119], v[120:121], v[226:227] op_sel_hi:[1,0,1]
	v_pk_fma_f32 v[228:229], v[116:117], v[120:121], v[228:229] op_sel:[0,1,0] op_sel_hi:[1,1,1]
	v_pk_fma_f32 v[230:231], v[118:119], v[120:121], v[230:231] op_sel:[0,1,0] op_sel_hi:[1,1,1]
	v_pk_fma_f32 v[12:13], v[12:13], v[192:193], v[224:225]
	v_pk_fma_f32 v[14:15], v[14:15], v[194:195], v[226:227]
	v_pk_fma_f32 v[28:29], v[28:29], v[192:193], v[228:229]
	v_pk_fma_f32 v[30:31], v[30:31], v[194:195], v[230:231]
	ds_read_b128 v[100:103], v232 offset:2864
	ds_read_b128 v[116:119], v232 offset:1840
	ds_read_b128 v[192:195], v232 offset:2352
	v_add_u32_e32 v232, 0x600, v232
	v_add_u32_e32 v233, 0x600, v233
	v_add_u32_e32 v234, 0x100, v234
	s_add_i32 s58, s58, 1
	s_cmp_lg_u32 s58, 16
	s_cbranch_scc1 .Lscan_step
	s_waitcnt lgkmcnt(13)
	v_pk_mul_f32 v[204:205], v[0:1], v[48:49]
	v_pk_mul_f32 v[208:209], v[16:17], v[48:49]
	s_nop 1
	v_pk_fma_f32 v[204:205], v[2:3], v[50:51], v[204:205]
	v_pk_fma_f32 v[208:209], v[18:19], v[50:51], v[208:209]
	s_nop 1
	v_pk_fma_f32 v[204:205], v[4:5], v[52:53], v[204:205]
	v_pk_fma_f32 v[208:209], v[20:21], v[52:53], v[208:209]
	s_nop 1
	v_pk_fma_f32 v[204:205], v[6:7], v[54:55], v[204:205]
	v_pk_fma_f32 v[208:209], v[22:23], v[54:55], v[208:209]
	s_nop 1
	v_pk_fma_f32 v[204:205], v[8:9], v[56:57], v[204:205]
	v_pk_fma_f32 v[208:209], v[24:25], v[56:57], v[208:209]
	s_nop 1
	v_pk_fma_f32 v[204:205], v[10:11], v[58:59], v[204:205]
	v_pk_fma_f32 v[208:209], v[26:27], v[58:59], v[208:209]
	s_nop 1
	v_pk_fma_f32 v[204:205], v[12:13], v[60:61], v[204:205]
	v_pk_fma_f32 v[208:209], v[28:29], v[60:61], v[208:209]
	s_nop 1
	v_pk_fma_f32 v[204:205], v[14:15], v[62:63], v[204:205]
	v_pk_fma_f32 v[208:209], v[30:31], v[62:63], v[208:209]
	s_nop 1
	s_nop 0
	v_add_f32_e32 v214, v204, v205
	v_add_f32_e32 v215, v208, v209
	s_nop 1
	v_add_f32_dpp v214, v214, v214 quad_perm:[1,0,3,2] row_mask:0xf bank_mask:0xf
	v_add_f32_dpp v215, v215, v215 quad_perm:[1,0,3,2] row_mask:0xf bank_mask:0xf
	s_nop 1
	v_add_f32_dpp v214, v214, v214 quad_perm:[2,3,0,1] row_mask:0xf bank_mask:0xf
	v_add_f32_dpp v215, v215, v215 quad_perm:[2,3,0,1] row_mask:0xf bank_mask:0xf
	s_nop 0
	ds_write_b64 v234, v[214:215]

; __device__ __forceinline__ unsigned pk_bf16(float lo, float hi) { const f32x2 v = {lo, hi}; return __builtin_bit_cast(unsigned, __builtin_convertvector(v, nbf16x2)); }
; __device__ __forceinline__ void st8_bf16(bf16_t* p, const f32x4 a, const f32x4 b) { __builtin_nontemporal_store((u32x4){pk_bf16(a[0], a[1]), pk_bf16(a[2], a[3]), pk_bf16(b[0], b[1]), pk_bf16(b[2], b[3])}, (u32x4*)p); }
; __device__ __forceinline__ void st8_f32(float* p, const f32x4 a, const f32x4 b) { __builtin_nontemporal_store(a, (f32x4*)p); __builtin_nontemporal_store(b, (f32x4*)(p + 4)); }
; __device__ __forceinline__ f32x4 silu4(const f32x4 v) { return (f32x4){v[0] / (1.f + __expf(-v[0])), v[1] / (1.f + __expf(-v[1])), v[2] / (1.f + __expf(-v[2])), v[3] / (1.f + __expf(-v[3]))}; }
;     __device__ __forceinline__ void store8(int row, int col, const f32x4 v, const f32x4 w) const {
;     ...
;         else st8_bf16((bf16_t*)(ws + WS_GATE) + (size_t)row * BR + (col - 5120), silu4(v), silu4(w));
.LBB0_733:
	s_lshl_b32 s35, s6, 8
	v_or_b32_e32 v148, s35, v154
	s_mov_b64 s[44:45], s[12:13]
	s_mov_b64 s[42:43], s[14:15]
	v_lshl_add_u32 v146, s8, 8, v152
	v_cmp_lt_i32_e64 s[8:9], s67, v148
	s_and_saveexec_b64 s[6:7], s[8:9]
	s_xor_b64 s[6:7], exec, s[6:7]
	s_cbranch_execz .LBB0_754
	s_cmpk_gt_u32 s35, 0xbff
	s_mov_b64 s[46:47], -1
	s_cbranch_scc0 .LBB0_748
	s_cmpk_gt_u32 s35, 0x11ff
	s_cbranch_scc0 .LBB0_741
	v_ashrrev_i32_e32 v147, 31, v146
	v_lshlrev_b64 v[150:151], 12, v[146:147]
	v_lshl_add_u64 v[150:151], s[42:43], 0, v[150:151]
	v_mov_b32_e32 v149, v137
	s_cmpk_gt_u32 s35, 0x13ff
	v_lshl_add_u64 v[150:151], v[148:149], 1, v[150:151]
	s_cbranch_scc0 .LBB0_738
	s_mov_b64 s[46:47], 0
	v_mul_f32_e32 v162, 0xbfb8aa3b, v122
	v_mul_f32_e32 v161, 0xbfb8aa3b, v123
	v_mul_f32_e32 v147, 0xbfb8aa3b, v124
	v_mul_f32_e32 v136, 0xbfb8aa3b, v125
	v_mul_f32_e32 v163, 0xbfb8aa3b, v126
	v_mul_f32_e32 v149, 0xbfb8aa3b, v127
	v_mul_f32_e32 v164, 0xbfb8aa3b, v120
	v_mul_f32_e32 v165, 0xbfb8aa3b, v121
	v_exp_f32_e32 v162, v162
	v_exp_f32_e32 v161, v161
	v_exp_f32_e32 v147, v147
	v_exp_f32_e32 v136, v136
	v_exp_f32_e32 v163, v163
	v_exp_f32_e32 v149, v149
	v_exp_f32_e32 v164, v164
	v_exp_f32_e32 v165, v165
	v_add_f32_e32 v162, 1.0, v162
	v_add_f32_e32 v161, 1.0, v161
	v_add_f32_e32 v147, 1.0, v147
	v_add_f32_e32 v136, 1.0, v136
	v_add_f32_e32 v163, 1.0, v163
	v_add_f32_e32 v149, 1.0, v149
	v_add_f32_e32 v164, 1.0, v164
	v_add_f32_e32 v165, 1.0, v165
	v_rcp_f32_e32 v162, v162
	v_rcp_f32_e32 v161, v161
	v_rcp_f32_e32 v147, v147
	v_rcp_f32_e32 v136, v136
	v_rcp_f32_e32 v163, v163
	v_rcp_f32_e32 v149, v149
	v_rcp_f32_e32 v164, v164
	v_rcp_f32_e32 v165, v165
	v_mul_f32_e32 v162, v122, v162
	v_mul_f32_e32 v161, v123, v161
	v_mul_f32_e32 v147, v124, v147
	v_mul_f32_e32 v136, v125, v136
	v_mul_f32_e32 v163, v126, v163
	v_mul_f32_e32 v149, v127, v149
	v_mul_f32_e32 v164, v120, v164
	v_mul_f32_e32 v165, v121, v165
	v_cvt_pk_bf16_f32 v161, v162, v161
	v_add_co_u32_e32 v162, vcc, 0x15add000, v150
	v_cvt_pk_bf16_f32 v158, v147, v136
	v_cvt_pk_bf16_f32 v159, v163, v149
	v_cvt_pk_bf16_f32 v160, v164, v165
	s_nop 1
	v_addc_co_u32_e32 v163, vcc, 0, v151, vcc
	flat_store_dwordx4 v[162:163], v[158:161] offset:2048 nt

; __device__ __forceinline__ unsigned pk_bf16(float lo, float hi) { const f32x2 v = {lo, hi}; return __builtin_bit_cast(unsigned, __builtin_convertvector(v, nbf16x2)); }
; __device__ __forceinline__ void st8_bf16(bf16_t* p, const f32x4 a, const f32x4 b) { __builtin_nontemporal_store((u32x4){pk_bf16(a[0], a[1]), pk_bf16(a[2], a[3]), pk_bf16(b[0], b[1]), pk_bf16(b[2], b[3])}, (u32x4*)p); }
; __device__ __forceinline__ void st8_f32(float* p, const f32x4 a, const f32x4 b) { __builtin_nontemporal_store(a, (f32x4*)p); __builtin_nontemporal_store(b, (f32x4*)(p + 4)); }
; __device__ __forceinline__ f32x4 silu4(const f32x4 v) { return (f32x4){v[0] / (1.f + __expf(-v[0])), v[1] / (1.f + __expf(-v[1])), v[2] / (1.f + __expf(-v[2])), v[3] / (1.f + __expf(-v[3]))}; }
;     __device__ __forceinline__ void store8(int row, int col, const f32x4 v, const f32x4 w) const {
;     ...
;         else st8_bf16((bf16_t*)(ws + WS_GATE) + (size_t)row * BR + (col - 5120), silu4(v), silu4(w));
.LBB0_756:
	s_or_b64 exec, exec, s[6:7]
	v_or_b32_e32 v120, 16, v146
	s_and_saveexec_b64 s[6:7], s[8:9]
	s_xor_b64 s[6:7], exec, s[6:7]
	s_cbranch_execz .LBB0_777
	s_cmpk_gt_u32 s35, 0xbff
	s_mov_b64 s[46:47], -1
	s_cbranch_scc0 .LBB0_771
	s_cmpk_gt_u32 s35, 0x11ff
	s_cbranch_scc0 .LBB0_764
	v_ashrrev_i32_e32 v121, 31, v120
	v_lshlrev_b64 v[122:123], 12, v[120:121]
	v_lshl_add_u64 v[122:123], s[42:43], 0, v[122:123]
	v_mov_b32_e32 v149, v137
	s_cmpk_gt_u32 s35, 0x13ff
	v_lshl_add_u64 v[122:123], v[148:149], 1, v[122:123]
	s_cbranch_scc0 .LBB0_761
	s_mov_b64 s[46:47], 0
	v_mul_f32_e32 v151, 0xbfb8aa3b, v118
	v_mul_f32_e32 v158, 0xbfb8aa3b, v119
	v_mul_f32_e32 v136, 0xbfb8aa3b, v116
	v_mul_f32_e32 v121, 0xbfb8aa3b, v117
	v_mul_f32_e32 v159, 0xbfb8aa3b, v112
	v_mul_f32_e32 v160, 0xbfb8aa3b, v113
	v_mul_f32_e32 v149, 0xbfb8aa3b, v114
	v_mul_f32_e32 v127, 0xbfb8aa3b, v115
	v_exp_f32_e32 v151, v151
	v_exp_f32_e32 v158, v158
	v_exp_f32_e32 v136, v136
	v_exp_f32_e32 v121, v121
	v_exp_f32_e32 v159, v159
	v_exp_f32_e32 v160, v160
	v_exp_f32_e32 v149, v149
	v_exp_f32_e32 v127, v127
	v_add_f32_e32 v151, 1.0, v151
	v_add_f32_e32 v158, 1.0, v158
	v_add_f32_e32 v136, 1.0, v136
	v_add_f32_e32 v121, 1.0, v121
	v_add_f32_e32 v159, 1.0, v159
	v_add_f32_e32 v160, 1.0, v160
	v_add_f32_e32 v149, 1.0, v149
	v_add_f32_e32 v127, 1.0, v127
	v_rcp_f32_e32 v151, v151
	v_rcp_f32_e32 v158, v158
	v_rcp_f32_e32 v136, v136
	v_rcp_f32_e32 v121, v121
	v_rcp_f32_e32 v159, v159
	v_rcp_f32_e32 v160, v160
	v_rcp_f32_e32 v149, v149
	v_rcp_f32_e32 v127, v127
	v_mul_f32_e32 v151, v118, v151
	v_mul_f32_e32 v158, v119, v158
	v_mul_f32_e32 v136, v116, v136
	v_mul_f32_e32 v121, v117, v121
	v_mul_f32_e32 v159, v112, v159
	v_mul_f32_e32 v160, v113, v160
	v_mul_f32_e32 v149, v114, v149
	v_mul_f32_e32 v127, v115, v127
	v_cvt_pk_bf16_f32 v125, v151, v158
	v_add_co_u32_e32 v158, vcc, 0x15add000, v122
	v_cvt_pk_bf16_f32 v124, v136, v121
	v_cvt_pk_bf16_f32 v126, v159, v160
	v_cvt_pk_bf16_f32 v127, v149, v127
	s_nop 1
	v_addc_co_u32_e32 v159, vcc, 0, v123, vcc
	flat_store_dwordx4 v[158:159], v[124:127] offset:2048 nt

; __device__ __forceinline__ unsigned pk_bf16(float lo, float hi) { const f32x2 v = {lo, hi}; return __builtin_bit_cast(unsigned, __builtin_convertvector(v, nbf16x2)); }
; __device__ __forceinline__ void st8_bf16(bf16_t* p, const f32x4 a, const f32x4 b) { __builtin_nontemporal_store((u32x4){pk_bf16(a[0], a[1]), pk_bf16(a[2], a[3]), pk_bf16(b[0], b[1]), pk_bf16(b[2], b[3])}, (u32x4*)p); }
; __device__ __forceinline__ void st8_f32(float* p, const f32x4 a, const f32x4 b) { __builtin_nontemporal_store(a, (f32x4*)p); __builtin_nontemporal_store(b, (f32x4*)(p + 4)); }
; __device__ __forceinline__ f32x4 silu4(const f32x4 v) { return (f32x4){v[0] / (1.f + __expf(-v[0])), v[1] / (1.f + __expf(-v[1])), v[2] / (1.f + __expf(-v[2])), v[3] / (1.f + __expf(-v[3]))}; }
;     __device__ __forceinline__ void store8(int row, int col, const f32x4 v, const f32x4 w) const {
;     ...
;         else st8_bf16((bf16_t*)(ws + WS_GATE) + (size_t)row * BR + (col - 5120), silu4(v), silu4(w));
.LBB0_779:
	s_or_b64 exec, exec, s[6:7]
	v_or_b32_e32 v112, 32, v146
	s_and_saveexec_b64 s[6:7], s[8:9]
	s_xor_b64 s[6:7], exec, s[6:7]
	s_cbranch_execz .LBB0_800
	s_cmpk_gt_u32 s35, 0xbff
	s_mov_b64 s[46:47], -1
	s_cbranch_scc0 .LBB0_794
	s_cmpk_gt_u32 s35, 0x11ff
	s_cbranch_scc0 .LBB0_787
	v_ashrrev_i32_e32 v113, 31, v112
	v_lshlrev_b64 v[114:115], 12, v[112:113]
	v_lshl_add_u64 v[114:115], s[42:43], 0, v[114:115]
	v_mov_b32_e32 v149, v137
	s_cmpk_gt_u32 s35, 0x13ff
	v_lshl_add_u64 v[114:115], v[148:149], 1, v[114:115]
	s_cbranch_scc0 .LBB0_784
	s_mov_b64 s[46:47], 0
	v_mul_f32_e32 v122, 0xbfb8aa3b, v108
	v_mul_f32_e32 v113, 0xbfb8aa3b, v109
	v_mul_f32_e32 v124, 0xbfb8aa3b, v110
	v_mul_f32_e32 v125, 0xbfb8aa3b, v111
	v_mul_f32_e32 v126, 0xbfb8aa3b, v104
	v_mul_f32_e32 v127, 0xbfb8aa3b, v105
	v_mul_f32_e32 v123, 0xbfb8aa3b, v106
	v_mul_f32_e32 v119, 0xbfb8aa3b, v107
	v_exp_f32_e32 v122, v122
	v_exp_f32_e32 v113, v113
	v_exp_f32_e32 v124, v124
	v_exp_f32_e32 v125, v125
	v_exp_f32_e32 v126, v126
	v_exp_f32_e32 v127, v127
	v_exp_f32_e32 v123, v123
	v_exp_f32_e32 v119, v119
	v_add_f32_e32 v122, 1.0, v122
	v_add_f32_e32 v113, 1.0, v113
	v_add_f32_e32 v124, 1.0, v124
	v_add_f32_e32 v125, 1.0, v125
	v_add_f32_e32 v126, 1.0, v126
	v_add_f32_e32 v127, 1.0, v127
	v_add_f32_e32 v123, 1.0, v123
	v_add_f32_e32 v119, 1.0, v119
	v_rcp_f32_e32 v122, v122
	v_rcp_f32_e32 v113, v113
	v_rcp_f32_e32 v124, v124
	v_rcp_f32_e32 v125, v125
	v_rcp_f32_e32 v126, v126
	v_rcp_f32_e32 v127, v127
	v_rcp_f32_e32 v123, v123
	v_rcp_f32_e32 v119, v119
	v_mul_f32_e32 v122, v108, v122
	v_mul_f32_e32 v113, v109, v113
	v_mul_f32_e32 v124, v110, v124
	v_mul_f32_e32 v125, v111, v125
	v_mul_f32_e32 v126, v104, v126
	v_mul_f32_e32 v127, v105, v127
	v_mul_f32_e32 v123, v106, v123
	v_mul_f32_e32 v119, v107, v119
	v_cvt_pk_bf16_f32 v116, v122, v113
	v_add_co_u32_e32 v122, vcc, 0x15add000, v114
	v_cvt_pk_bf16_f32 v117, v124, v125
	v_cvt_pk_bf16_f32 v118, v126, v127
	v_cvt_pk_bf16_f32 v119, v123, v119
	s_nop 1
	v_addc_co_u32_e32 v123, vcc, 0, v115, vcc
	flat_store_dwordx4 v[122:123], v[116:119] offset:2048 nt

; __device__ __forceinline__ unsigned pk_bf16(float lo, float hi) { const f32x2 v = {lo, hi}; return __builtin_bit_cast(unsigned, __builtin_convertvector(v, nbf16x2)); }
; __device__ __forceinline__ void st8_bf16(bf16_t* p, const f32x4 a, const f32x4 b) { __builtin_nontemporal_store((u32x4){pk_bf16(a[0], a[1]), pk_bf16(a[2], a[3]), pk_bf16(b[0], b[1]), pk_bf16(b[2], b[3])}, (u32x4*)p); }
; __device__ __forceinline__ void st8_f32(float* p, const f32x4 a, const f32x4 b) { __builtin_nontemporal_store(a, (f32x4*)p); __builtin_nontemporal_store(b, (f32x4*)(p + 4)); }
; __device__ __forceinline__ f32x4 silu4(const f32x4 v) { return (f32x4){v[0] / (1.f + __expf(-v[0])), v[1] / (1.f + __expf(-v[1])), v[2] / (1.f + __expf(-v[2])), v[3] / (1.f + __expf(-v[3]))}; }
;     __device__ __forceinline__ void store8(int row, int col, const f32x4 v, const f32x4 w) const {
;     ...
;         else st8_bf16((bf16_t*)(ws + WS_GATE) + (size_t)row * BR + (col - 5120), silu4(v), silu4(w));
.LBB0_802:
	s_or_b64 exec, exec, s[6:7]
	v_or_b32_e32 v104, 48, v146
	s_and_saveexec_b64 s[6:7], s[8:9]
	s_xor_b64 s[6:7], exec, s[6:7]
	s_cbranch_execz .LBB0_823
	s_cmpk_gt_u32 s35, 0xbff
	s_mov_b64 s[46:47], -1
	s_cbranch_scc0 .LBB0_817
	s_cmpk_gt_u32 s35, 0x11ff
	s_cbranch_scc0 .LBB0_810
	v_ashrrev_i32_e32 v105, 31, v104
	v_lshlrev_b64 v[106:107], 12, v[104:105]
	v_lshl_add_u64 v[106:107], s[42:43], 0, v[106:107]
	v_mov_b32_e32 v149, v137
	s_cmpk_gt_u32 s35, 0x13ff
	v_lshl_add_u64 v[106:107], v[148:149], 1, v[106:107]
	s_cbranch_scc0 .LBB0_807
	s_mov_b64 s[46:47], 0
	v_mul_f32_e32 v114, 0xbfb8aa3b, v100
	v_mul_f32_e32 v105, 0xbfb8aa3b, v101
	v_mul_f32_e32 v116, 0xbfb8aa3b, v102
	v_mul_f32_e32 v117, 0xbfb8aa3b, v103
	v_mul_f32_e32 v118, 0xbfb8aa3b, v96
	v_mul_f32_e32 v119, 0xbfb8aa3b, v97
	v_mul_f32_e32 v115, 0xbfb8aa3b, v98
	v_mul_f32_e32 v111, 0xbfb8aa3b, v99
	v_exp_f32_e32 v114, v114
	v_exp_f32_e32 v105, v105
	v_exp_f32_e32 v116, v116
	v_exp_f32_e32 v117, v117
	v_exp_f32_e32 v118, v118
	v_exp_f32_e32 v119, v119
	v_exp_f32_e32 v115, v115
	v_exp_f32_e32 v111, v111
	v_add_f32_e32 v114, 1.0, v114
	v_add_f32_e32 v105, 1.0, v105
	v_add_f32_e32 v116, 1.0, v116
	v_add_f32_e32 v117, 1.0, v117
	v_add_f32_e32 v118, 1.0, v118
	v_add_f32_e32 v119, 1.0, v119
	v_add_f32_e32 v115, 1.0, v115
	v_add_f32_e32 v111, 1.0, v111
	v_rcp_f32_e32 v114, v114
	v_rcp_f32_e32 v105, v105
	v_rcp_f32_e32 v116, v116
	v_rcp_f32_e32 v117, v117
	v_rcp_f32_e32 v118, v118
	v_rcp_f32_e32 v119, v119
	v_rcp_f32_e32 v115, v115
	v_rcp_f32_e32 v111, v111
	v_mul_f32_e32 v114, v100, v114
	v_mul_f32_e32 v105, v101, v105
	v_mul_f32_e32 v116, v102, v116
	v_mul_f32_e32 v117, v103, v117
	v_mul_f32_e32 v118, v96, v118
	v_mul_f32_e32 v119, v97, v119
	v_mul_f32_e32 v115, v98, v115
	v_mul_f32_e32 v111, v99, v111
	v_cvt_pk_bf16_f32 v108, v114, v105
	v_add_co_u32_e32 v114, vcc, 0x15add000, v106
	v_cvt_pk_bf16_f32 v109, v116, v117
	v_cvt_pk_bf16_f32 v110, v118, v119
	v_cvt_pk_bf16_f32 v111, v115, v111
	s_nop 1
	v_addc_co_u32_e32 v115, vcc, 0, v107, vcc
	flat_store_dwordx4 v[114:115], v[108:111] offset:2048 nt

; __device__ __forceinline__ unsigned pk_bf16(float lo, float hi) { const f32x2 v = {lo, hi}; return __builtin_bit_cast(unsigned, __builtin_convertvector(v, nbf16x2)); }
; __device__ __forceinline__ void st8_bf16(bf16_t* p, const f32x4 a, const f32x4 b) { __builtin_nontemporal_store((u32x4){pk_bf16(a[0], a[1]), pk_bf16(a[2], a[3]), pk_bf16(b[0], b[1]), pk_bf16(b[2], b[3])}, (u32x4*)p); }
; __device__ __forceinline__ void st8_f32(float* p, const f32x4 a, const f32x4 b) { __builtin_nontemporal_store(a, (f32x4*)p); __builtin_nontemporal_store(b, (f32x4*)(p + 4)); }
; __device__ __forceinline__ f32x4 silu4(const f32x4 v) { return (f32x4){v[0] / (1.f + __expf(-v[0])), v[1] / (1.f + __expf(-v[1])), v[2] / (1.f + __expf(-v[2])), v[3] / (1.f + __expf(-v[3]))}; }
;     __device__ __forceinline__ void store8(int row, int col, const f32x4 v, const f32x4 w) const {
;     ...
;         else st8_bf16((bf16_t*)(ws + WS_GATE) + (size_t)row * BR + (col - 5120), silu4(v), silu4(w));
.LBB0_825:
	s_or_b64 exec, exec, s[6:7]
	v_or_b32_e32 v96, 0x80, v148
	v_cmp_lt_i32_e64 s[6:7], s67, v96
	s_and_saveexec_b64 s[46:47], s[6:7]
	s_xor_b64 s[46:47], exec, s[46:47]
	s_cbranch_execz .LBB0_846
	s_cmpk_gt_u32 s35, 0xbff
	s_mov_b64 s[50:51], -1
	s_cbranch_scc0 .LBB0_840
	s_cmpk_gt_u32 s35, 0x11ff
	s_cbranch_scc0 .LBB0_833
	v_lshlrev_b64 v[96:97], 12, v[146:147]
	v_lshl_add_u64 v[96:97], s[42:43], 0, v[96:97]
	v_mov_b32_e32 v149, v137
	v_lshl_add_u64 v[96:97], v[148:149], 1, v[96:97]
	s_cmpk_gt_u32 s35, 0x13ff
	v_lshl_add_u64 v[96:97], v[96:97], 0, s[22:23]
	s_cbranch_scc0 .LBB0_830
	s_mov_b64 s[50:51], 0
	v_mul_f32_e32 v102, 0xbfb8aa3b, v90
	v_mul_f32_e32 v101, 0xbfb8aa3b, v91
	v_mul_f32_e32 v106, 0xbfb8aa3b, v92
	v_mul_f32_e32 v103, 0xbfb8aa3b, v93
	v_mul_f32_e32 v107, 0xbfb8aa3b, v94
	v_mul_f32_e32 v108, 0xbfb8aa3b, v95
	v_mul_f32_e32 v109, 0xbfb8aa3b, v88
	v_mul_f32_e32 v110, 0xbfb8aa3b, v89
	v_exp_f32_e32 v102, v102
	v_exp_f32_e32 v101, v101
	v_exp_f32_e32 v106, v106
	v_exp_f32_e32 v103, v103
	v_exp_f32_e32 v107, v107
	v_exp_f32_e32 v108, v108
	v_exp_f32_e32 v109, v109
	v_exp_f32_e32 v110, v110
	v_add_f32_e32 v102, 1.0, v102
	v_add_f32_e32 v101, 1.0, v101
	v_add_f32_e32 v106, 1.0, v106
	v_add_f32_e32 v103, 1.0, v103
	v_add_f32_e32 v107, 1.0, v107
	v_add_f32_e32 v108, 1.0, v108
	v_add_f32_e32 v109, 1.0, v109
	v_add_f32_e32 v110, 1.0, v110
	v_rcp_f32_e32 v102, v102
	v_rcp_f32_e32 v101, v101
	v_rcp_f32_e32 v106, v106
	v_rcp_f32_e32 v103, v103
	v_rcp_f32_e32 v107, v107
	v_rcp_f32_e32 v108, v108
	v_rcp_f32_e32 v109, v109
	v_rcp_f32_e32 v110, v110
	v_mul_f32_e32 v102, v90, v102
	v_mul_f32_e32 v101, v91, v101
	v_mul_f32_e32 v106, v92, v106
	v_mul_f32_e32 v103, v93, v103
	v_mul_f32_e32 v107, v94, v107
	v_mul_f32_e32 v108, v95, v108
	v_mul_f32_e32 v109, v88, v109
	v_mul_f32_e32 v110, v89, v110
	v_cvt_pk_bf16_f32 v101, v102, v101
	v_add_co_u32_e32 v102, vcc, 0x15add000, v96
	v_cvt_pk_bf16_f32 v98, v106, v103
	v_cvt_pk_bf16_f32 v99, v107, v108
	v_cvt_pk_bf16_f32 v100, v109, v110
	s_nop 1
	v_addc_co_u32_e32 v103, vcc, 0, v97, vcc
	flat_store_dwordx4 v[102:103], v[98:101] offset:2048 nt

; __device__ __forceinline__ unsigned pk_bf16(float lo, float hi) { const f32x2 v = {lo, hi}; return __builtin_bit_cast(unsigned, __builtin_convertvector(v, nbf16x2)); }
; __device__ __forceinline__ void st8_bf16(bf16_t* p, const f32x4 a, const f32x4 b) { __builtin_nontemporal_store((u32x4){pk_bf16(a[0], a[1]), pk_bf16(a[2], a[3]), pk_bf16(b[0], b[1]), pk_bf16(b[2], b[3])}, (u32x4*)p); }
; __device__ __forceinline__ void st8_f32(float* p, const f32x4 a, const f32x4 b) { __builtin_nontemporal_store(a, (f32x4*)p); __builtin_nontemporal_store(b, (f32x4*)(p + 4)); }
; __device__ __forceinline__ f32x4 silu4(const f32x4 v) { return (f32x4){v[0] / (1.f + __expf(-v[0])), v[1] / (1.f + __expf(-v[1])), v[2] / (1.f + __expf(-v[2])), v[3] / (1.f + __expf(-v[3]))}; }
;     __device__ __forceinline__ void store8(int row, int col, const f32x4 v, const f32x4 w) const {
;     ...
;         else st8_bf16((bf16_t*)(ws + WS_GATE) + (size_t)row * BR + (col - 5120), silu4(v), silu4(w));
.LBB0_848:
	s_or_b64 exec, exec, s[46:47]
	s_and_saveexec_b64 s[46:47], s[6:7]
	s_xor_b64 s[46:47], exec, s[46:47]
	s_cbranch_execz .LBB0_869
	s_cmpk_gt_u32 s35, 0xbff
	s_mov_b64 s[50:51], -1
	s_cbranch_scc0 .LBB0_863
	s_cmpk_gt_u32 s35, 0x11ff
	s_cbranch_scc0 .LBB0_856
	v_lshlrev_b64 v[88:89], 12, v[120:121]
	v_lshl_add_u64 v[88:89], s[42:43], 0, v[88:89]
	v_mov_b32_e32 v149, v137
	v_lshl_add_u64 v[88:89], v[148:149], 1, v[88:89]
	s_cmpk_gt_u32 s35, 0x13ff
	v_lshl_add_u64 v[88:89], v[88:89], 0, s[22:23]
	s_cbranch_scc0 .LBB0_853
	s_mov_b64 s[50:51], 0
	v_mul_f32_e32 v94, 0xbfb8aa3b, v82
	v_mul_f32_e32 v93, 0xbfb8aa3b, v83
	v_mul_f32_e32 v96, 0xbfb8aa3b, v84
	v_mul_f32_e32 v95, 0xbfb8aa3b, v85
	v_mul_f32_e32 v97, 0xbfb8aa3b, v86
	v_mul_f32_e32 v98, 0xbfb8aa3b, v87
	v_mul_f32_e32 v99, 0xbfb8aa3b, v80
	v_mul_f32_e32 v100, 0xbfb8aa3b, v81
	v_exp_f32_e32 v94, v94
	v_exp_f32_e32 v93, v93
	v_exp_f32_e32 v96, v96
	v_exp_f32_e32 v95, v95
	v_exp_f32_e32 v97, v97
	v_exp_f32_e32 v98, v98
	v_exp_f32_e32 v99, v99
	v_exp_f32_e32 v100, v100
	v_add_f32_e32 v94, 1.0, v94
	v_add_f32_e32 v93, 1.0, v93
	v_add_f32_e32 v96, 1.0, v96
	v_add_f32_e32 v95, 1.0, v95
	v_add_f32_e32 v97, 1.0, v97
	v_add_f32_e32 v98, 1.0, v98
	v_add_f32_e32 v99, 1.0, v99
	v_add_f32_e32 v100, 1.0, v100
	v_rcp_f32_e32 v94, v94
	v_rcp_f32_e32 v93, v93
	v_rcp_f32_e32 v96, v96
	v_rcp_f32_e32 v95, v95
	v_rcp_f32_e32 v97, v97
	v_rcp_f32_e32 v98, v98
	v_rcp_f32_e32 v99, v99
	v_rcp_f32_e32 v100, v100
	v_mul_f32_e32 v94, v82, v94
	v_mul_f32_e32 v93, v83, v93
	v_mul_f32_e32 v96, v84, v96
	v_mul_f32_e32 v95, v85, v95
	v_mul_f32_e32 v97, v86, v97
	v_mul_f32_e32 v98, v87, v98
	v_mul_f32_e32 v99, v80, v99
	v_mul_f32_e32 v100, v81, v100
	v_cvt_pk_bf16_f32 v93, v94, v93
	v_add_co_u32_e32 v94, vcc, 0x15add000, v88
	v_cvt_pk_bf16_f32 v90, v96, v95
	v_cvt_pk_bf16_f32 v91, v97, v98
	v_cvt_pk_bf16_f32 v92, v99, v100
	s_nop 1
	v_addc_co_u32_e32 v95, vcc, 0, v89, vcc
	flat_store_dwordx4 v[94:95], v[90:93] offset:2048 nt

; __device__ __forceinline__ unsigned pk_bf16(float lo, float hi) { const f32x2 v = {lo, hi}; return __builtin_bit_cast(unsigned, __builtin_convertvector(v, nbf16x2)); }
; __device__ __forceinline__ void st8_bf16(bf16_t* p, const f32x4 a, const f32x4 b) { __builtin_nontemporal_store((u32x4){pk_bf16(a[0], a[1]), pk_bf16(a[2], a[3]), pk_bf16(b[0], b[1]), pk_bf16(b[2], b[3])}, (u32x4*)p); }
; __device__ __forceinline__ void st8_f32(float* p, const f32x4 a, const f32x4 b) { __builtin_nontemporal_store(a, (f32x4*)p); __builtin_nontemporal_store(b, (f32x4*)(p + 4)); }
; __device__ __forceinline__ f32x4 silu4(const f32x4 v) { return (f32x4){v[0] / (1.f + __expf(-v[0])), v[1] / (1.f + __expf(-v[1])), v[2] / (1.f + __expf(-v[2])), v[3] / (1.f + __expf(-v[3]))}; }
;     __device__ __forceinline__ void store8(int row, int col, const f32x4 v, const f32x4 w) const {
;     ...
;         else st8_bf16((bf16_t*)(ws + WS_GATE) + (size_t)row * BR + (col - 5120), silu4(v), silu4(w));
.LBB0_871:
	s_or_b64 exec, exec, s[46:47]
	s_and_saveexec_b64 s[46:47], s[6:7]
	s_xor_b64 s[46:47], exec, s[46:47]
	s_cbranch_execz .LBB0_892
	s_cmpk_gt_u32 s35, 0xbff
	s_mov_b64 s[50:51], -1
	s_cbranch_scc0 .LBB0_886
	s_cmpk_gt_u32 s35, 0x11ff
	s_cbranch_scc0 .LBB0_879
	v_lshlrev_b64 v[80:81], 12, v[112:113]
	v_lshl_add_u64 v[80:81], s[42:43], 0, v[80:81]
	v_mov_b32_e32 v149, v137
	v_lshl_add_u64 v[80:81], v[148:149], 1, v[80:81]
	s_cmpk_gt_u32 s35, 0x13ff
	v_lshl_add_u64 v[80:81], v[80:81], 0, s[22:23]
	s_cbranch_scc0 .LBB0_876
	s_mov_b64 s[50:51], 0
	v_mul_f32_e32 v86, 0xbfb8aa3b, v74
	v_mul_f32_e32 v85, 0xbfb8aa3b, v75
	v_mul_f32_e32 v88, 0xbfb8aa3b, v76
	v_mul_f32_e32 v87, 0xbfb8aa3b, v77
	v_mul_f32_e32 v89, 0xbfb8aa3b, v78
	v_mul_f32_e32 v90, 0xbfb8aa3b, v79
	v_mul_f32_e32 v91, 0xbfb8aa3b, v72
	v_mul_f32_e32 v92, 0xbfb8aa3b, v73
	v_exp_f32_e32 v86, v86
	v_exp_f32_e32 v85, v85
	v_exp_f32_e32 v88, v88
	v_exp_f32_e32 v87, v87
	v_exp_f32_e32 v89, v89
	v_exp_f32_e32 v90, v90
	v_exp_f32_e32 v91, v91
	v_exp_f32_e32 v92, v92
	v_add_f32_e32 v86, 1.0, v86
	v_add_f32_e32 v85, 1.0, v85
	v_add_f32_e32 v88, 1.0, v88
	v_add_f32_e32 v87, 1.0, v87
	v_add_f32_e32 v89, 1.0, v89
	v_add_f32_e32 v90, 1.0, v90
	v_add_f32_e32 v91, 1.0, v91
	v_add_f32_e32 v92, 1.0, v92
	v_rcp_f32_e32 v86, v86
	v_rcp_f32_e32 v85, v85
	v_rcp_f32_e32 v88, v88
	v_rcp_f32_e32 v87, v87
	v_rcp_f32_e32 v89, v89
	v_rcp_f32_e32 v90, v90
	v_rcp_f32_e32 v91, v91
	v_rcp_f32_e32 v92, v92
	v_mul_f32_e32 v86, v74, v86
	v_mul_f32_e32 v85, v75, v85
	v_mul_f32_e32 v88, v76, v88
	v_mul_f32_e32 v87, v77, v87
	v_mul_f32_e32 v89, v78, v89
	v_mul_f32_e32 v90, v79, v90
	v_mul_f32_e32 v91, v72, v91
	v_mul_f32_e32 v92, v73, v92
	v_cvt_pk_bf16_f32 v85, v86, v85
	v_add_co_u32_e32 v86, vcc, 0x15add000, v80
	v_cvt_pk_bf16_f32 v82, v88, v87
	v_cvt_pk_bf16_f32 v83, v89, v90
	v_cvt_pk_bf16_f32 v84, v91, v92
	s_nop 1
	v_addc_co_u32_e32 v87, vcc, 0, v81, vcc
	flat_store_dwordx4 v[86:87], v[82:85] offset:2048 nt

; __device__ __forceinline__ unsigned pk_bf16(float lo, float hi) { const f32x2 v = {lo, hi}; return __builtin_bit_cast(unsigned, __builtin_convertvector(v, nbf16x2)); }
; __device__ __forceinline__ void st8_bf16(bf16_t* p, const f32x4 a, const f32x4 b) { __builtin_nontemporal_store((u32x4){pk_bf16(a[0], a[1]), pk_bf16(a[2], a[3]), pk_bf16(b[0], b[1]), pk_bf16(b[2], b[3])}, (u32x4*)p); }
; __device__ __forceinline__ void st8_f32(float* p, const f32x4 a, const f32x4 b) { __builtin_nontemporal_store(a, (f32x4*)p); __builtin_nontemporal_store(b, (f32x4*)(p + 4)); }
; __device__ __forceinline__ f32x4 silu4(const f32x4 v) { return (f32x4){v[0] / (1.f + __expf(-v[0])), v[1] / (1.f + __expf(-v[1])), v[2] / (1.f + __expf(-v[2])), v[3] / (1.f + __expf(-v[3]))}; }
;     __device__ __forceinline__ void store8(int row, int col, const f32x4 v, const f32x4 w) const {
;     ...
;         else st8_bf16((bf16_t*)(ws + WS_GATE) + (size_t)row * BR + (col - 5120), silu4(v), silu4(w));
.LBB0_894:
	s_or_b64 exec, exec, s[46:47]
	s_and_saveexec_b64 s[46:47], s[6:7]
	s_xor_b64 s[46:47], exec, s[46:47]
	s_cbranch_execz .LBB0_915
	s_cmpk_gt_u32 s35, 0xbff
	s_mov_b64 s[50:51], -1
	s_cbranch_scc0 .LBB0_909
	s_cmpk_gt_u32 s35, 0x11ff
	s_cbranch_scc0 .LBB0_902
	v_lshlrev_b64 v[72:73], 12, v[104:105]
	v_lshl_add_u64 v[72:73], s[42:43], 0, v[72:73]
	v_mov_b32_e32 v149, v137
	v_lshl_add_u64 v[72:73], v[148:149], 1, v[72:73]
	s_cmpk_gt_u32 s35, 0x13ff
	v_lshl_add_u64 v[72:73], v[72:73], 0, s[22:23]
	s_cbranch_scc0 .LBB0_899
	s_mov_b64 s[50:51], 0
	v_mul_f32_e32 v78, 0xbfb8aa3b, v66
	v_mul_f32_e32 v77, 0xbfb8aa3b, v67
	v_mul_f32_e32 v80, 0xbfb8aa3b, v68
	v_mul_f32_e32 v79, 0xbfb8aa3b, v69
	v_mul_f32_e32 v81, 0xbfb8aa3b, v70
	v_mul_f32_e32 v82, 0xbfb8aa3b, v71
	v_mul_f32_e32 v83, 0xbfb8aa3b, v64
	v_mul_f32_e32 v84, 0xbfb8aa3b, v65
	v_exp_f32_e32 v78, v78
	v_exp_f32_e32 v77, v77
	v_exp_f32_e32 v80, v80
	v_exp_f32_e32 v79, v79
	v_exp_f32_e32 v81, v81
	v_exp_f32_e32 v82, v82
	v_exp_f32_e32 v83, v83
	v_exp_f32_e32 v84, v84
	v_add_f32_e32 v78, 1.0, v78
	v_add_f32_e32 v77, 1.0, v77
	v_add_f32_e32 v80, 1.0, v80
	v_add_f32_e32 v79, 1.0, v79
	v_add_f32_e32 v81, 1.0, v81
	v_add_f32_e32 v82, 1.0, v82
	v_add_f32_e32 v83, 1.0, v83
	v_add_f32_e32 v84, 1.0, v84
	v_rcp_f32_e32 v78, v78
	v_rcp_f32_e32 v77, v77
	v_rcp_f32_e32 v80, v80
	v_rcp_f32_e32 v79, v79
	v_rcp_f32_e32 v81, v81
	v_rcp_f32_e32 v82, v82
	v_rcp_f32_e32 v83, v83
	v_rcp_f32_e32 v84, v84
	v_mul_f32_e32 v78, v66, v78
	v_mul_f32_e32 v77, v67, v77
	v_mul_f32_e32 v80, v68, v80
	v_mul_f32_e32 v79, v69, v79
	v_mul_f32_e32 v81, v70, v81
	v_mul_f32_e32 v82, v71, v82
	v_mul_f32_e32 v83, v64, v83
	v_mul_f32_e32 v84, v65, v84
	v_cvt_pk_bf16_f32 v77, v78, v77
	v_add_co_u32_e32 v78, vcc, 0x15add000, v72
	v_cvt_pk_bf16_f32 v74, v80, v79
	v_cvt_pk_bf16_f32 v75, v81, v82
	v_cvt_pk_bf16_f32 v76, v83, v84
	s_nop 1
	v_addc_co_u32_e32 v79, vcc, 0, v73, vcc
	flat_store_dwordx4 v[78:79], v[74:77] offset:2048 nt

; __device__ __forceinline__ unsigned pk_bf16(float lo, float hi) { const f32x2 v = {lo, hi}; return __builtin_bit_cast(unsigned, __builtin_convertvector(v, nbf16x2)); }
; __device__ __forceinline__ void st8_bf16(bf16_t* p, const f32x4 a, const f32x4 b) { __builtin_nontemporal_store((u32x4){pk_bf16(a[0], a[1]), pk_bf16(a[2], a[3]), pk_bf16(b[0], b[1]), pk_bf16(b[2], b[3])}, (u32x4*)p); }
; __device__ __forceinline__ void st8_f32(float* p, const f32x4 a, const f32x4 b) { __builtin_nontemporal_store(a, (f32x4*)p); __builtin_nontemporal_store(b, (f32x4*)(p + 4)); }
; __device__ __forceinline__ f32x4 silu4(const f32x4 v) { return (f32x4){v[0] / (1.f + __expf(-v[0])), v[1] / (1.f + __expf(-v[1])), v[2] / (1.f + __expf(-v[2])), v[3] / (1.f + __expf(-v[3]))}; }
;     __device__ __forceinline__ void store8(int row, int col, const f32x4 v, const f32x4 w) const {
;     ...
;         else st8_bf16((bf16_t*)(ws + WS_GATE) + (size_t)row * BR + (col - 5120), silu4(v), silu4(w));
.LBB0_917:
	s_or_b64 exec, exec, s[46:47]
	v_add_u32_e32 v64, 0x80, v146
	s_and_saveexec_b64 s[46:47], s[8:9]
	s_xor_b64 s[46:47], exec, s[46:47]
	s_cbranch_execz .LBB0_938
	s_cmpk_gt_u32 s35, 0xbff
	s_mov_b64 s[50:51], -1
	s_cbranch_scc0 .LBB0_932
	s_cmpk_gt_u32 s35, 0x11ff
	s_cbranch_scc0 .LBB0_925
	v_ashrrev_i32_e32 v65, 31, v64
	v_lshlrev_b64 v[66:67], 12, v[64:65]
	v_lshl_add_u64 v[66:67], s[42:43], 0, v[66:67]
	v_mov_b32_e32 v149, v137
	s_cmpk_gt_u32 s35, 0x13ff
	v_lshl_add_u64 v[66:67], v[148:149], 1, v[66:67]
	s_cbranch_scc0 .LBB0_922
	s_mov_b64 s[50:51], 0
	v_mul_f32_e32 v72, 0xbfb8aa3b, v60
	v_mul_f32_e32 v65, 0xbfb8aa3b, v61
	v_mul_f32_e32 v74, 0xbfb8aa3b, v62
	v_mul_f32_e32 v75, 0xbfb8aa3b, v63
	v_mul_f32_e32 v76, 0xbfb8aa3b, v56
	v_mul_f32_e32 v77, 0xbfb8aa3b, v57
	v_mul_f32_e32 v73, 0xbfb8aa3b, v58
	v_mul_f32_e32 v71, 0xbfb8aa3b, v59
	v_exp_f32_e32 v72, v72
	v_exp_f32_e32 v65, v65
	v_exp_f32_e32 v74, v74
	v_exp_f32_e32 v75, v75
	v_exp_f32_e32 v76, v76
	v_exp_f32_e32 v77, v77
	v_exp_f32_e32 v73, v73
	v_exp_f32_e32 v71, v71
	v_add_f32_e32 v72, 1.0, v72
	v_add_f32_e32 v65, 1.0, v65
	v_add_f32_e32 v74, 1.0, v74
	v_add_f32_e32 v75, 1.0, v75
	v_add_f32_e32 v76, 1.0, v76
	v_add_f32_e32 v77, 1.0, v77
	v_add_f32_e32 v73, 1.0, v73
	v_add_f32_e32 v71, 1.0, v71
	v_rcp_f32_e32 v72, v72
	v_rcp_f32_e32 v65, v65
	v_rcp_f32_e32 v74, v74
	v_rcp_f32_e32 v75, v75
	v_rcp_f32_e32 v76, v76
	v_rcp_f32_e32 v77, v77
	v_rcp_f32_e32 v73, v73
	v_rcp_f32_e32 v71, v71
	v_mul_f32_e32 v72, v60, v72
	v_mul_f32_e32 v65, v61, v65
	v_mul_f32_e32 v74, v62, v74
	v_mul_f32_e32 v75, v63, v75
	v_mul_f32_e32 v76, v56, v76
	v_mul_f32_e32 v77, v57, v77
	v_mul_f32_e32 v73, v58, v73
	v_mul_f32_e32 v71, v59, v71
	v_cvt_pk_bf16_f32 v68, v72, v65
	v_add_co_u32_e32 v72, vcc, 0x15add000, v66
	v_cvt_pk_bf16_f32 v69, v74, v75
	v_cvt_pk_bf16_f32 v70, v76, v77
	v_cvt_pk_bf16_f32 v71, v73, v71
	s_nop 1
	v_addc_co_u32_e32 v73, vcc, 0, v67, vcc
	flat_store_dwordx4 v[72:73], v[68:71] offset:2048 nt

; __device__ __forceinline__ unsigned pk_bf16(float lo, float hi) { const f32x2 v = {lo, hi}; return __builtin_bit_cast(unsigned, __builtin_convertvector(v, nbf16x2)); }
; __device__ __forceinline__ void st8_bf16(bf16_t* p, const f32x4 a, const f32x4 b) { __builtin_nontemporal_store((u32x4){pk_bf16(a[0], a[1]), pk_bf16(a[2], a[3]), pk_bf16(b[0], b[1]), pk_bf16(b[2], b[3])}, (u32x4*)p); }
; __device__ __forceinline__ void st8_f32(float* p, const f32x4 a, const f32x4 b) { __builtin_nontemporal_store(a, (f32x4*)p); __builtin_nontemporal_store(b, (f32x4*)(p + 4)); }
; __device__ __forceinline__ f32x4 silu4(const f32x4 v) { return (f32x4){v[0] / (1.f + __expf(-v[0])), v[1] / (1.f + __expf(-v[1])), v[2] / (1.f + __expf(-v[2])), v[3] / (1.f + __expf(-v[3]))}; }
;     __device__ __forceinline__ void store8(int row, int col, const f32x4 v, const f32x4 w) const {
;     ...
;         else st8_bf16((bf16_t*)(ws + WS_GATE) + (size_t)row * BR + (col - 5120), silu4(v), silu4(w));
.LBB0_940:
	s_or_b64 exec, exec, s[46:47]
	v_add_u32_e32 v56, 0x90, v146
	s_and_saveexec_b64 s[46:47], s[8:9]
	s_xor_b64 s[46:47], exec, s[46:47]
	s_cbranch_execz .LBB0_961
	s_cmpk_gt_u32 s35, 0xbff
	s_mov_b64 s[50:51], -1
	s_cbranch_scc0 .LBB0_955
	s_cmpk_gt_u32 s35, 0x11ff
	s_cbranch_scc0 .LBB0_948
	v_ashrrev_i32_e32 v57, 31, v56
	v_lshlrev_b64 v[58:59], 12, v[56:57]
	v_lshl_add_u64 v[58:59], s[42:43], 0, v[58:59]
	v_mov_b32_e32 v149, v137
	s_cmpk_gt_u32 s35, 0x13ff
	v_lshl_add_u64 v[58:59], v[148:149], 1, v[58:59]
	s_cbranch_scc0 .LBB0_945
	s_mov_b64 s[50:51], 0
	v_mul_f32_e32 v66, 0xbfb8aa3b, v52
	v_mul_f32_e32 v57, 0xbfb8aa3b, v53
	v_mul_f32_e32 v68, 0xbfb8aa3b, v54
	v_mul_f32_e32 v69, 0xbfb8aa3b, v55
	v_mul_f32_e32 v70, 0xbfb8aa3b, v48
	v_mul_f32_e32 v71, 0xbfb8aa3b, v49
	v_mul_f32_e32 v67, 0xbfb8aa3b, v50
	v_mul_f32_e32 v63, 0xbfb8aa3b, v51
	v_exp_f32_e32 v66, v66
	v_exp_f32_e32 v57, v57
	v_exp_f32_e32 v68, v68
	v_exp_f32_e32 v69, v69
	v_exp_f32_e32 v70, v70
	v_exp_f32_e32 v71, v71
	v_exp_f32_e32 v67, v67
	v_exp_f32_e32 v63, v63
	v_add_f32_e32 v66, 1.0, v66
	v_add_f32_e32 v57, 1.0, v57
	v_add_f32_e32 v68, 1.0, v68
	v_add_f32_e32 v69, 1.0, v69
	v_add_f32_e32 v70, 1.0, v70
	v_add_f32_e32 v71, 1.0, v71
	v_add_f32_e32 v67, 1.0, v67
	v_add_f32_e32 v63, 1.0, v63
	v_rcp_f32_e32 v66, v66
	v_rcp_f32_e32 v57, v57
	v_rcp_f32_e32 v68, v68
	v_rcp_f32_e32 v69, v69
	v_rcp_f32_e32 v70, v70
	v_rcp_f32_e32 v71, v71
	v_rcp_f32_e32 v67, v67
	v_rcp_f32_e32 v63, v63
	v_mul_f32_e32 v66, v52, v66
	v_mul_f32_e32 v57, v53, v57
	v_mul_f32_e32 v68, v54, v68
	v_mul_f32_e32 v69, v55, v69
	v_mul_f32_e32 v70, v48, v70
	v_mul_f32_e32 v71, v49, v71
	v_mul_f32_e32 v67, v50, v67
	v_mul_f32_e32 v63, v51, v63
	v_cvt_pk_bf16_f32 v60, v66, v57
	v_add_co_u32_e32 v66, vcc, 0x15add000, v58
	v_cvt_pk_bf16_f32 v61, v68, v69
	v_cvt_pk_bf16_f32 v62, v70, v71
	v_cvt_pk_bf16_f32 v63, v67, v63
	s_nop 1
	v_addc_co_u32_e32 v67, vcc, 0, v59, vcc
	flat_store_dwordx4 v[66:67], v[60:63] offset:2048 nt

; __device__ __forceinline__ unsigned pk_bf16(float lo, float hi) { const f32x2 v = {lo, hi}; return __builtin_bit_cast(unsigned, __builtin_convertvector(v, nbf16x2)); }
; __device__ __forceinline__ void st8_bf16(bf16_t* p, const f32x4 a, const f32x4 b) { __builtin_nontemporal_store((u32x4){pk_bf16(a[0], a[1]), pk_bf16(a[2], a[3]), pk_bf16(b[0], b[1]), pk_bf16(b[2], b[3])}, (u32x4*)p); }
; __device__ __forceinline__ void st8_f32(float* p, const f32x4 a, const f32x4 b) { __builtin_nontemporal_store(a, (f32x4*)p); __builtin_nontemporal_store(b, (f32x4*)(p + 4)); }
; __device__ __forceinline__ f32x4 silu4(const f32x4 v) { return (f32x4){v[0] / (1.f + __expf(-v[0])), v[1] / (1.f + __expf(-v[1])), v[2] / (1.f + __expf(-v[2])), v[3] / (1.f + __expf(-v[3]))}; }
;     __device__ __forceinline__ void store8(int row, int col, const f32x4 v, const f32x4 w) const {
;     ...
;         else st8_bf16((bf16_t*)(ws + WS_GATE) + (size_t)row * BR + (col - 5120), silu4(v), silu4(w));
.LBB0_963:
	s_or_b64 exec, exec, s[46:47]
	v_add_u32_e32 v48, 0xa0, v146
	s_and_saveexec_b64 s[46:47], s[8:9]
	s_xor_b64 s[46:47], exec, s[46:47]
	s_cbranch_execz .LBB0_984
	s_cmpk_gt_u32 s35, 0xbff
	s_mov_b64 s[50:51], -1
	s_cbranch_scc0 .LBB0_978
	s_cmpk_gt_u32 s35, 0x11ff
	s_cbranch_scc0 .LBB0_971
	v_ashrrev_i32_e32 v49, 31, v48
	v_lshlrev_b64 v[50:51], 12, v[48:49]
	v_lshl_add_u64 v[50:51], s[42:43], 0, v[50:51]
	v_mov_b32_e32 v149, v137
	s_cmpk_gt_u32 s35, 0x13ff
	v_lshl_add_u64 v[50:51], v[148:149], 1, v[50:51]
	s_cbranch_scc0 .LBB0_968
	s_mov_b64 s[50:51], 0
	v_mul_f32_e32 v58, 0xbfb8aa3b, v44
	v_mul_f32_e32 v49, 0xbfb8aa3b, v45
	v_mul_f32_e32 v60, 0xbfb8aa3b, v46
	v_mul_f32_e32 v61, 0xbfb8aa3b, v47
	v_mul_f32_e32 v62, 0xbfb8aa3b, v40
	v_mul_f32_e32 v63, 0xbfb8aa3b, v41
	v_mul_f32_e32 v59, 0xbfb8aa3b, v42
	v_mul_f32_e32 v55, 0xbfb8aa3b, v43
	v_exp_f32_e32 v58, v58
	v_exp_f32_e32 v49, v49
	v_exp_f32_e32 v60, v60
	v_exp_f32_e32 v61, v61
	v_exp_f32_e32 v62, v62
	v_exp_f32_e32 v63, v63
	v_exp_f32_e32 v59, v59
	v_exp_f32_e32 v55, v55
	v_add_f32_e32 v58, 1.0, v58
	v_add_f32_e32 v49, 1.0, v49
	v_add_f32_e32 v60, 1.0, v60
	v_add_f32_e32 v61, 1.0, v61
	v_add_f32_e32 v62, 1.0, v62
	v_add_f32_e32 v63, 1.0, v63
	v_add_f32_e32 v59, 1.0, v59
	v_add_f32_e32 v55, 1.0, v55
	v_rcp_f32_e32 v58, v58
	v_rcp_f32_e32 v49, v49
	v_rcp_f32_e32 v60, v60
	v_rcp_f32_e32 v61, v61
	v_rcp_f32_e32 v62, v62
	v_rcp_f32_e32 v63, v63
	v_rcp_f32_e32 v59, v59
	v_rcp_f32_e32 v55, v55
	v_mul_f32_e32 v58, v44, v58
	v_mul_f32_e32 v49, v45, v49
	v_mul_f32_e32 v60, v46, v60
	v_mul_f32_e32 v61, v47, v61
	v_mul_f32_e32 v62, v40, v62
	v_mul_f32_e32 v63, v41, v63
	v_mul_f32_e32 v59, v42, v59
	v_mul_f32_e32 v55, v43, v55
	v_cvt_pk_bf16_f32 v52, v58, v49
	v_add_co_u32_e32 v58, vcc, 0x15add000, v50
	v_cvt_pk_bf16_f32 v53, v60, v61
	v_cvt_pk_bf16_f32 v54, v62, v63
	v_cvt_pk_bf16_f32 v55, v59, v55
	s_nop 1
	v_addc_co_u32_e32 v59, vcc, 0, v51, vcc
	flat_store_dwordx4 v[58:59], v[52:55] offset:2048 nt

; __device__ __forceinline__ unsigned pk_bf16(float lo, float hi) { const f32x2 v = {lo, hi}; return __builtin_bit_cast(unsigned, __builtin_convertvector(v, nbf16x2)); }
; __device__ __forceinline__ void st8_bf16(bf16_t* p, const f32x4 a, const f32x4 b) { __builtin_nontemporal_store((u32x4){pk_bf16(a[0], a[1]), pk_bf16(a[2], a[3]), pk_bf16(b[0], b[1]), pk_bf16(b[2], b[3])}, (u32x4*)p); }
; __device__ __forceinline__ void st8_f32(float* p, const f32x4 a, const f32x4 b) { __builtin_nontemporal_store(a, (f32x4*)p); __builtin_nontemporal_store(b, (f32x4*)(p + 4)); }
; __device__ __forceinline__ f32x4 silu4(const f32x4 v) { return (f32x4){v[0] / (1.f + __expf(-v[0])), v[1] / (1.f + __expf(-v[1])), v[2] / (1.f + __expf(-v[2])), v[3] / (1.f + __expf(-v[3]))}; }
;     __device__ __forceinline__ void store8(int row, int col, const f32x4 v, const f32x4 w) const {
;     ...
;         else st8_bf16((bf16_t*)(ws + WS_GATE) + (size_t)row * BR + (col - 5120), silu4(v), silu4(w));
.LBB0_986:
	s_or_b64 exec, exec, s[46:47]
	v_add_u32_e32 v40, 0xb0, v146
	s_and_saveexec_b64 s[46:47], s[8:9]
	s_xor_b64 s[8:9], exec, s[46:47]
	s_cbranch_execz .LBB0_1007
	s_cmpk_gt_u32 s35, 0xbff
	s_mov_b64 s[46:47], -1
	s_cbranch_scc0 .LBB0_1001
	s_cmpk_gt_u32 s35, 0x11ff
	s_cbranch_scc0 .LBB0_994
	v_ashrrev_i32_e32 v41, 31, v40
	v_lshlrev_b64 v[42:43], 12, v[40:41]
	v_lshl_add_u64 v[42:43], s[42:43], 0, v[42:43]
	v_mov_b32_e32 v149, v137
	s_cmpk_gt_u32 s35, 0x13ff
	v_lshl_add_u64 v[42:43], v[148:149], 1, v[42:43]
	s_cbranch_scc0 .LBB0_991
	s_mov_b64 s[46:47], 0
	v_mul_f32_e32 v50, 0xbfb8aa3b, v36
	v_mul_f32_e32 v41, 0xbfb8aa3b, v37
	v_mul_f32_e32 v52, 0xbfb8aa3b, v38
	v_mul_f32_e32 v53, 0xbfb8aa3b, v39
	v_mul_f32_e32 v54, 0xbfb8aa3b, v32
	v_mul_f32_e32 v55, 0xbfb8aa3b, v33
	v_mul_f32_e32 v51, 0xbfb8aa3b, v34
	v_mul_f32_e32 v47, 0xbfb8aa3b, v35
	v_exp_f32_e32 v50, v50
	v_exp_f32_e32 v41, v41
	v_exp_f32_e32 v52, v52
	v_exp_f32_e32 v53, v53
	v_exp_f32_e32 v54, v54
	v_exp_f32_e32 v55, v55
	v_exp_f32_e32 v51, v51
	v_exp_f32_e32 v47, v47
	v_add_f32_e32 v50, 1.0, v50
	v_add_f32_e32 v41, 1.0, v41
	v_add_f32_e32 v52, 1.0, v52
	v_add_f32_e32 v53, 1.0, v53
	v_add_f32_e32 v54, 1.0, v54
	v_add_f32_e32 v55, 1.0, v55
	v_add_f32_e32 v51, 1.0, v51
	v_add_f32_e32 v47, 1.0, v47
	v_rcp_f32_e32 v50, v50
	v_rcp_f32_e32 v41, v41
	v_rcp_f32_e32 v52, v52
	v_rcp_f32_e32 v53, v53
	v_rcp_f32_e32 v54, v54
	v_rcp_f32_e32 v55, v55
	v_rcp_f32_e32 v51, v51
	v_rcp_f32_e32 v47, v47
	v_mul_f32_e32 v50, v36, v50
	v_mul_f32_e32 v41, v37, v41
	v_mul_f32_e32 v52, v38, v52
	v_mul_f32_e32 v53, v39, v53
	v_mul_f32_e32 v54, v32, v54
	v_mul_f32_e32 v55, v33, v55
	v_mul_f32_e32 v51, v34, v51
	v_mul_f32_e32 v47, v35, v47
	v_cvt_pk_bf16_f32 v44, v50, v41
	v_add_co_u32_e32 v50, vcc, 0x15add000, v42
	v_cvt_pk_bf16_f32 v45, v52, v53
	v_cvt_pk_bf16_f32 v46, v54, v55
	v_cvt_pk_bf16_f32 v47, v51, v47
	s_nop 1
	v_addc_co_u32_e32 v51, vcc, 0, v43, vcc
	flat_store_dwordx4 v[50:51], v[44:47] offset:2048 nt

; __device__ __forceinline__ unsigned pk_bf16(float lo, float hi) { const f32x2 v = {lo, hi}; return __builtin_bit_cast(unsigned, __builtin_convertvector(v, nbf16x2)); }
; __device__ __forceinline__ void st8_bf16(bf16_t* p, const f32x4 a, const f32x4 b) { __builtin_nontemporal_store((u32x4){pk_bf16(a[0], a[1]), pk_bf16(a[2], a[3]), pk_bf16(b[0], b[1]), pk_bf16(b[2], b[3])}, (u32x4*)p); }
; __device__ __forceinline__ void st8_f32(float* p, const f32x4 a, const f32x4 b) { __builtin_nontemporal_store(a, (f32x4*)p); __builtin_nontemporal_store(b, (f32x4*)(p + 4)); }
; __device__ __forceinline__ f32x4 silu4(const f32x4 v) { return (f32x4){v[0] / (1.f + __expf(-v[0])), v[1] / (1.f + __expf(-v[1])), v[2] / (1.f + __expf(-v[2])), v[3] / (1.f + __expf(-v[3]))}; }
;     __device__ __forceinline__ void store8(int row, int col, const f32x4 v, const f32x4 w) const {
;     ...
;         else st8_bf16((bf16_t*)(ws + WS_GATE) + (size_t)row * BR + (col - 5120), silu4(v), silu4(w));
.LBB0_1009:
	s_or_b64 exec, exec, s[8:9]
	s_and_saveexec_b64 s[8:9], s[6:7]
	s_xor_b64 s[8:9], exec, s[8:9]
	s_cbranch_execz .LBB0_1030
	s_cmpk_gt_u32 s35, 0xbff
	s_mov_b64 s[46:47], -1
	s_cbranch_scc0 .LBB0_1024
	s_cmpk_gt_u32 s35, 0x11ff
	s_cbranch_scc0 .LBB0_1017
	v_lshlrev_b64 v[32:33], 12, v[64:65]
	v_lshl_add_u64 v[32:33], s[42:43], 0, v[32:33]
	v_mov_b32_e32 v149, v137
	v_lshl_add_u64 v[32:33], v[148:149], 1, v[32:33]
	s_cmpk_gt_u32 s35, 0x13ff
	v_lshl_add_u64 v[32:33], v[32:33], 0, s[22:23]
	s_cbranch_scc0 .LBB0_1014
	s_mov_b64 s[46:47], 0
	v_mul_f32_e32 v38, 0xbfb8aa3b, v26
	v_mul_f32_e32 v37, 0xbfb8aa3b, v27
	v_mul_f32_e32 v42, 0xbfb8aa3b, v28
	v_mul_f32_e32 v39, 0xbfb8aa3b, v29
	v_mul_f32_e32 v43, 0xbfb8aa3b, v30
	v_mul_f32_e32 v44, 0xbfb8aa3b, v31
	v_mul_f32_e32 v45, 0xbfb8aa3b, v24
	v_mul_f32_e32 v46, 0xbfb8aa3b, v25
	v_exp_f32_e32 v38, v38
	v_exp_f32_e32 v37, v37
	v_exp_f32_e32 v42, v42
	v_exp_f32_e32 v39, v39
	v_exp_f32_e32 v43, v43
	v_exp_f32_e32 v44, v44
	v_exp_f32_e32 v45, v45
	v_exp_f32_e32 v46, v46
	v_add_f32_e32 v38, 1.0, v38
	v_add_f32_e32 v37, 1.0, v37
	v_add_f32_e32 v42, 1.0, v42
	v_add_f32_e32 v39, 1.0, v39
	v_add_f32_e32 v43, 1.0, v43
	v_add_f32_e32 v44, 1.0, v44
	v_add_f32_e32 v45, 1.0, v45
	v_add_f32_e32 v46, 1.0, v46
	v_rcp_f32_e32 v38, v38
	v_rcp_f32_e32 v37, v37
	v_rcp_f32_e32 v42, v42
	v_rcp_f32_e32 v39, v39
	v_rcp_f32_e32 v43, v43
	v_rcp_f32_e32 v44, v44
	v_rcp_f32_e32 v45, v45
	v_rcp_f32_e32 v46, v46
	v_mul_f32_e32 v38, v26, v38
	v_mul_f32_e32 v37, v27, v37
	v_mul_f32_e32 v42, v28, v42
	v_mul_f32_e32 v39, v29, v39
	v_mul_f32_e32 v43, v30, v43
	v_mul_f32_e32 v44, v31, v44
	v_mul_f32_e32 v45, v24, v45
	v_mul_f32_e32 v46, v25, v46
	v_cvt_pk_bf16_f32 v37, v38, v37
	v_add_co_u32_e32 v38, vcc, 0x15add000, v32
	v_cvt_pk_bf16_f32 v34, v42, v39
	v_cvt_pk_bf16_f32 v35, v43, v44
	v_cvt_pk_bf16_f32 v36, v45, v46
	s_nop 1
	v_addc_co_u32_e32 v39, vcc, 0, v33, vcc
	flat_store_dwordx4 v[38:39], v[34:37] offset:2048 nt

; __device__ __forceinline__ void st8_bf16(bf16_t* p, const f32x4 a, const f32x4 b) { __builtin_nontemporal_store((u32x4){pk_bf16(a[0], a[1]), pk_bf16(a[2], a[3]), pk_bf16(b[0], b[1]), pk_bf16(b[2], b[3])}, (u32x4*)p); }
; __device__ __forceinline__ void st8_f32(float* p, const f32x4 a, const f32x4 b) { __builtin_nontemporal_store(a, (f32x4*)p); __builtin_nontemporal_store(b, (f32x4*)(p + 4)); }
; __device__ __forceinline__ f32x4 silu4(const f32x4 v) { return (f32x4){v[0] / (1.f + __expf(-v[0])), v[1] / (1.f + __expf(-v[1])), v[2] / (1.f + __expf(-v[2])), v[3] / (1.f + __expf(-v[3]))}; }
;     __device__ __forceinline__ void store8(int row, int col, const f32x4 v, const f32x4 w) const {
;         if (col < 1536) st8_bf16((bf16_t*)(ws + WS_BRANCH) + (size_t)row * BR + col, v, w);
;         else if (col < 3072) { const int c = col - 1536; st8_bf16((bf16_t*)(ws + WS_KB) + (size_t)row * MIXW + c, v, w);
;             if (row < MP) st8_f32(out + O_PK + (size_t)row * MIXW + c, v, w); else st8_f32(out + O_SK + (size_t)(row - MP) * MIXW + c, v, w); }
;         else if (col < 4608) { const int c = col - 3072; st8_bf16((bf16_t*)(ws + WS_VB) + (size_t)row * MIXW + c, v, w);
;             if (row < MP) st8_f32(out + O_PV + (size_t)row * MIXW + c, v, w); else st8_f32(out + O_SV + (size_t)(row - MP) * MIXW + c, v, w); }
;         else if (col < 5120) st8_bf16((bf16_t*)(ws + WS_BRANCH) + (size_t)row * BR + 1536 + (col - 4608), v, w);
;         else st8_bf16((bf16_t*)(ws + WS_GATE) + (size_t)row * BR + (col - 5120), silu4(v), silu4(w));
.LBB0_1032:
	s_or_b64 exec, exec, s[8:9]
	s_and_saveexec_b64 s[8:9], s[6:7]
	s_xor_b64 s[8:9], exec, s[8:9]
	s_cbranch_execz .LBB0_1053
	s_cmpk_gt_u32 s35, 0xbff
	s_mov_b64 s[46:47], -1
	s_cbranch_scc0 .LBB0_1047
	s_cmpk_gt_u32 s35, 0x11ff
	s_cbranch_scc0 .LBB0_1040
	v_lshlrev_b64 v[24:25], 12, v[56:57]
	v_lshl_add_u64 v[24:25], s[42:43], 0, v[24:25]
	v_mov_b32_e32 v149, v137
	v_lshl_add_u64 v[24:25], v[148:149], 1, v[24:25]
	s_cmpk_gt_u32 s35, 0x13ff
	v_lshl_add_u64 v[24:25], v[24:25], 0, s[22:23]
	s_cbranch_scc0 .LBB0_1037
	s_mov_b64 s[46:47], 0
	v_mul_f32_e32 v30, 0xbfb8aa3b, v18
	v_mul_f32_e32 v29, 0xbfb8aa3b, v19
	v_mul_f32_e32 v32, 0xbfb8aa3b, v20
	v_mul_f32_e32 v31, 0xbfb8aa3b, v21
	v_mul_f32_e32 v33, 0xbfb8aa3b, v22
	v_mul_f32_e32 v34, 0xbfb8aa3b, v23
	v_mul_f32_e32 v35, 0xbfb8aa3b, v16
	v_mul_f32_e32 v36, 0xbfb8aa3b, v17
	v_exp_f32_e32 v30, v30
	v_exp_f32_e32 v29, v29
	v_exp_f32_e32 v32, v32
	v_exp_f32_e32 v31, v31
	v_exp_f32_e32 v33, v33
	v_exp_f32_e32 v34, v34
	v_exp_f32_e32 v35, v35
	v_exp_f32_e32 v36, v36
	v_add_f32_e32 v30, 1.0, v30
	v_add_f32_e32 v29, 1.0, v29
	v_add_f32_e32 v32, 1.0, v32
	v_add_f32_e32 v31, 1.0, v31
	v_add_f32_e32 v33, 1.0, v33
	v_add_f32_e32 v34, 1.0, v34
	v_add_f32_e32 v35, 1.0, v35
	v_add_f32_e32 v36, 1.0, v36
	v_rcp_f32_e32 v30, v30
	v_rcp_f32_e32 v29, v29
	v_rcp_f32_e32 v32, v32
	v_rcp_f32_e32 v31, v31
	v_rcp_f32_e32 v33, v33
	v_rcp_f32_e32 v34, v34
	v_rcp_f32_e32 v35, v35
	v_rcp_f32_e32 v36, v36
	v_mul_f32_e32 v30, v18, v30
	v_mul_f32_e32 v29, v19, v29
	v_mul_f32_e32 v32, v20, v32
	v_mul_f32_e32 v31, v21, v31
	v_mul_f32_e32 v33, v22, v33
	v_mul_f32_e32 v34, v23, v34
	v_mul_f32_e32 v35, v16, v35
	v_mul_f32_e32 v36, v17, v36
	v_cvt_pk_bf16_f32 v29, v30, v29
	v_add_co_u32_e32 v30, vcc, 0x15add000, v24
	v_cvt_pk_bf16_f32 v26, v32, v31
	v_cvt_pk_bf16_f32 v27, v33, v34
	v_cvt_pk_bf16_f32 v28, v35, v36
	s_nop 1
	v_addc_co_u32_e32 v31, vcc, 0, v25, vcc
	flat_store_dwordx4 v[30:31], v[26:29] offset:2048 nt

; __device__ __forceinline__ void st8_bf16(bf16_t* p, const f32x4 a, const f32x4 b) { __builtin_nontemporal_store((u32x4){pk_bf16(a[0], a[1]), pk_bf16(a[2], a[3]), pk_bf16(b[0], b[1]), pk_bf16(b[2], b[3])}, (u32x4*)p); }
; __device__ __forceinline__ void st8_f32(float* p, const f32x4 a, const f32x4 b) { __builtin_nontemporal_store(a, (f32x4*)p); __builtin_nontemporal_store(b, (f32x4*)(p + 4)); }
; __device__ __forceinline__ f32x4 silu4(const f32x4 v) { return (f32x4){v[0] / (1.f + __expf(-v[0])), v[1] / (1.f + __expf(-v[1])), v[2] / (1.f + __expf(-v[2])), v[3] / (1.f + __expf(-v[3]))}; }
;     __device__ __forceinline__ void store8(int row, int col, const f32x4 v, const f32x4 w) const {
;         if (col < 1536) st8_bf16((bf16_t*)(ws + WS_BRANCH) + (size_t)row * BR + col, v, w);
;         else if (col < 3072) { const int c = col - 1536; st8_bf16((bf16_t*)(ws + WS_KB) + (size_t)row * MIXW + c, v, w);
;             if (row < MP) st8_f32(out + O_PK + (size_t)row * MIXW + c, v, w); else st8_f32(out + O_SK + (size_t)(row - MP) * MIXW + c, v, w); }
;         else if (col < 4608) { const int c = col - 3072; st8_bf16((bf16_t*)(ws + WS_VB) + (size_t)row * MIXW + c, v, w);
;             if (row < MP) st8_f32(out + O_PV + (size_t)row * MIXW + c, v, w); else st8_f32(out + O_SV + (size_t)(row - MP) * MIXW + c, v, w); }
;         else if (col < 5120) st8_bf16((bf16_t*)(ws + WS_BRANCH) + (size_t)row * BR + 1536 + (col - 4608), v, w);
;         else st8_bf16((bf16_t*)(ws + WS_GATE) + (size_t)row * BR + (col - 5120), silu4(v), silu4(w));
.LBB0_1055:
	s_or_b64 exec, exec, s[8:9]
	s_and_saveexec_b64 s[8:9], s[6:7]
	s_xor_b64 s[8:9], exec, s[8:9]
	s_cbranch_execz .LBB0_1076
	s_cmpk_gt_u32 s35, 0xbff
	s_mov_b64 s[46:47], -1
	s_cbranch_scc0 .LBB0_1070
	s_cmpk_gt_u32 s35, 0x11ff
	s_cbranch_scc0 .LBB0_1063
	v_lshlrev_b64 v[16:17], 12, v[48:49]
	v_lshl_add_u64 v[16:17], s[42:43], 0, v[16:17]
	v_mov_b32_e32 v149, v137
	v_lshl_add_u64 v[16:17], v[148:149], 1, v[16:17]
	s_cmpk_gt_u32 s35, 0x13ff
	v_lshl_add_u64 v[16:17], v[16:17], 0, s[22:23]
	s_cbranch_scc0 .LBB0_1060
	s_mov_b64 s[46:47], 0
	v_mul_f32_e32 v22, 0xbfb8aa3b, v10
	v_mul_f32_e32 v21, 0xbfb8aa3b, v11
	v_mul_f32_e32 v24, 0xbfb8aa3b, v12
	v_mul_f32_e32 v23, 0xbfb8aa3b, v13
	v_mul_f32_e32 v25, 0xbfb8aa3b, v14
	v_mul_f32_e32 v26, 0xbfb8aa3b, v15
	v_mul_f32_e32 v27, 0xbfb8aa3b, v8
	v_mul_f32_e32 v28, 0xbfb8aa3b, v9
	v_exp_f32_e32 v22, v22
	v_exp_f32_e32 v21, v21
	v_exp_f32_e32 v24, v24
	v_exp_f32_e32 v23, v23
	v_exp_f32_e32 v25, v25
	v_exp_f32_e32 v26, v26
	v_exp_f32_e32 v27, v27
	v_exp_f32_e32 v28, v28
	v_add_f32_e32 v22, 1.0, v22
	v_add_f32_e32 v21, 1.0, v21
	v_add_f32_e32 v24, 1.0, v24
	v_add_f32_e32 v23, 1.0, v23
	v_add_f32_e32 v25, 1.0, v25
	v_add_f32_e32 v26, 1.0, v26
	v_add_f32_e32 v27, 1.0, v27
	v_add_f32_e32 v28, 1.0, v28
	v_rcp_f32_e32 v22, v22
	v_rcp_f32_e32 v21, v21
	v_rcp_f32_e32 v24, v24
	v_rcp_f32_e32 v23, v23
	v_rcp_f32_e32 v25, v25
	v_rcp_f32_e32 v26, v26
	v_rcp_f32_e32 v27, v27
	v_rcp_f32_e32 v28, v28
	v_mul_f32_e32 v22, v10, v22
	v_mul_f32_e32 v21, v11, v21
	v_mul_f32_e32 v24, v12, v24
	v_mul_f32_e32 v23, v13, v23
	v_mul_f32_e32 v25, v14, v25
	v_mul_f32_e32 v26, v15, v26
	v_mul_f32_e32 v27, v8, v27
	v_mul_f32_e32 v28, v9, v28
	v_cvt_pk_bf16_f32 v21, v22, v21
	v_add_co_u32_e32 v22, vcc, 0x15add000, v16
	v_cvt_pk_bf16_f32 v18, v24, v23
	v_cvt_pk_bf16_f32 v19, v25, v26
	v_cvt_pk_bf16_f32 v20, v27, v28
	s_nop 1
	v_addc_co_u32_e32 v23, vcc, 0, v17, vcc
	flat_store_dwordx4 v[22:23], v[18:21] offset:2048 nt

; __device__ __forceinline__ void st8_bf16(bf16_t* p, const f32x4 a, const f32x4 b) { __builtin_nontemporal_store((u32x4){pk_bf16(a[0], a[1]), pk_bf16(a[2], a[3]), pk_bf16(b[0], b[1]), pk_bf16(b[2], b[3])}, (u32x4*)p); }
; __device__ __forceinline__ void st8_f32(float* p, const f32x4 a, const f32x4 b) { __builtin_nontemporal_store(a, (f32x4*)p); __builtin_nontemporal_store(b, (f32x4*)(p + 4)); }
; __device__ __forceinline__ f32x4 silu4(const f32x4 v) { return (f32x4){v[0] / (1.f + __expf(-v[0])), v[1] / (1.f + __expf(-v[1])), v[2] / (1.f + __expf(-v[2])), v[3] / (1.f + __expf(-v[3]))}; }
;     __device__ __forceinline__ void store8(int row, int col, const f32x4 v, const f32x4 w) const {
;         if (col < 1536) st8_bf16((bf16_t*)(ws + WS_BRANCH) + (size_t)row * BR + col, v, w);
;         else if (col < 3072) { const int c = col - 1536; st8_bf16((bf16_t*)(ws + WS_KB) + (size_t)row * MIXW + c, v, w);
;             if (row < MP) st8_f32(out + O_PK + (size_t)row * MIXW + c, v, w); else st8_f32(out + O_SK + (size_t)(row - MP) * MIXW + c, v, w); }
;         else if (col < 4608) { const int c = col - 3072; st8_bf16((bf16_t*)(ws + WS_VB) + (size_t)row * MIXW + c, v, w);
;             if (row < MP) st8_f32(out + O_PV + (size_t)row * MIXW + c, v, w); else st8_f32(out + O_SV + (size_t)(row - MP) * MIXW + c, v, w); }
;         else if (col < 5120) st8_bf16((bf16_t*)(ws + WS_BRANCH) + (size_t)row * BR + 1536 + (col - 4608), v, w);
;         else st8_bf16((bf16_t*)(ws + WS_GATE) + (size_t)row * BR + (col - 5120), silu4(v), silu4(w));
.LBB0_1078:
	s_or_b64 exec, exec, s[8:9]
	s_and_saveexec_b64 s[8:9], s[6:7]
	s_xor_b64 s[6:7], exec, s[8:9]
	s_cbranch_execz .LBB0_1099
	s_cmpk_gt_u32 s35, 0xbff
	s_mov_b64 s[8:9], -1
	s_cbranch_scc0 .LBB0_1093
	s_cmpk_gt_u32 s35, 0x11ff
	s_cbranch_scc0 .LBB0_1086
	v_lshlrev_b64 v[8:9], 12, v[40:41]
	v_lshl_add_u64 v[8:9], s[42:43], 0, v[8:9]
	v_mov_b32_e32 v149, v137
	v_lshl_add_u64 v[8:9], v[148:149], 1, v[8:9]
	s_cmpk_gt_u32 s35, 0x13ff
	v_lshl_add_u64 v[8:9], v[8:9], 0, s[22:23]
	s_cbranch_scc0 .LBB0_1083
	s_mov_b64 s[8:9], 0
	v_mul_f32_e32 v14, 0xbfb8aa3b, v2
	v_mul_f32_e32 v13, 0xbfb8aa3b, v3
	v_mul_f32_e32 v16, 0xbfb8aa3b, v4
	v_mul_f32_e32 v15, 0xbfb8aa3b, v5
	v_mul_f32_e32 v17, 0xbfb8aa3b, v6
	v_mul_f32_e32 v18, 0xbfb8aa3b, v7
	v_mul_f32_e32 v19, 0xbfb8aa3b, v0
	v_mul_f32_e32 v20, 0xbfb8aa3b, v1
	v_exp_f32_e32 v14, v14
	v_exp_f32_e32 v13, v13
	v_exp_f32_e32 v16, v16
	v_exp_f32_e32 v15, v15
	v_exp_f32_e32 v17, v17
	v_exp_f32_e32 v18, v18
	v_exp_f32_e32 v19, v19
	v_exp_f32_e32 v20, v20
	v_add_f32_e32 v14, 1.0, v14
	v_add_f32_e32 v13, 1.0, v13
	v_add_f32_e32 v16, 1.0, v16
	v_add_f32_e32 v15, 1.0, v15
	v_add_f32_e32 v17, 1.0, v17
	v_add_f32_e32 v18, 1.0, v18
	v_add_f32_e32 v19, 1.0, v19
	v_add_f32_e32 v20, 1.0, v20
	v_rcp_f32_e32 v14, v14
	v_rcp_f32_e32 v13, v13
	v_rcp_f32_e32 v16, v16
	v_rcp_f32_e32 v15, v15
	v_rcp_f32_e32 v17, v17
	v_rcp_f32_e32 v18, v18
	v_rcp_f32_e32 v19, v19
	v_rcp_f32_e32 v20, v20
	v_mul_f32_e32 v14, v2, v14
	v_mul_f32_e32 v13, v3, v13
	v_mul_f32_e32 v16, v4, v16
	v_mul_f32_e32 v15, v5, v15
	v_mul_f32_e32 v17, v6, v17
	v_mul_f32_e32 v18, v7, v18
	v_mul_f32_e32 v19, v0, v19
	v_mul_f32_e32 v20, v1, v20
	v_cvt_pk_bf16_f32 v13, v14, v13
	v_add_co_u32_e32 v14, vcc, 0x15add000, v8
	v_cvt_pk_bf16_f32 v10, v16, v15
	v_cvt_pk_bf16_f32 v11, v17, v18
	v_cvt_pk_bf16_f32 v12, v19, v20
	s_nop 1
	v_addc_co_u32_e32 v15, vcc, 0, v9, vcc
	flat_store_dwordx4 v[14:15], v[10:13] offset:2048 nt

; template <int NS, int SI>
; __device__ __forceinline__ void attn_stream(const unsigned char* kbase, const unsigned char* vbase, const unsigned char* q_rd, bool mask_tail, int last_valid, int hh, float sc,
;                                             f32x16 (&O)[4], float& mrun, float& lrun) {
;     ...
;     float mx = __builtin_amdgcn_fmed3f(S0[0], S1[0], __builtin_inff());
; #pragma unroll
;     for (int r = 1; r < 16; ++r) { mx = __builtin_amdgcn_fmed3f(mx, S0[r], __builtin_inff()); mx = __builtin_amdgcn_fmed3f(mx, S1[r], __builtin_inff()); }
;     mx = fmaxf(mx, __shfl_xor(mx, 32));
;     const float mn = fmaxf(mrun, mx * sc);
;     const float alpha = __builtin_amdgcn_exp2f(mrun - mn);
;     mrun = mn;
;     f32x2 ls2 = {0.f, 0.f};
;     const f32x2 sc2 = {sc, sc}, mn2 = {mn, mn};
; #pragma unroll
;     for (int r = 0; r < 16; r += 2) {
;         const f32x2 t0 = (f32x2){S0[r], S0[r + 1]} * sc2 - mn2, t1 = (f32x2){S1[r], S1[r + 1]} * sc2 - mn2;
;         const f32x2 p0 = {__builtin_amdgcn_exp2f(t0.x), __builtin_amdgcn_exp2f(t0.y)}, p1 = {__builtin_amdgcn_exp2f(t1.x), __builtin_amdgcn_exp2f(t1.y)};
;         S0[r] = p0.x; S0[r + 1] = p0.y; S1[r] = p1.x; S1[r + 1] = p1.y; ls2 += p0 + p1;
;     }
;     lrun = lrun * alpha + (ls2.x + ls2.y);
;     if (__any(alpha != 1.0f)) {
; #pragma unroll
;         for (int d = 0; d < 4; ++d) O[d] = O[d] * alpha;
;     }
.LBB0_1165:
	s_nop 9
	v_max_f32_e32 v200, v144, v144
	v_max_f32_e32 v202, v128, v128
	v_max_f32_e32 v200, v202, v200
	v_max3_f32 v200, v200, v129, v145
	v_max3_f32 v200, v200, v130, v146
	v_max3_f32 v200, v200, v131, v147
	v_max3_f32 v200, v200, v132, v148
	v_max3_f32 v200, v200, v133, v149
	v_max3_f32 v200, v200, v134, v150
	v_max3_f32 v200, v200, v135, v151
	v_max3_f32 v200, v200, v136, v152
	v_max3_f32 v200, v200, v137, v153
	v_max3_f32 v200, v200, v138, v154
	v_max3_f32 v200, v200, v139, v155
	v_and_b32_e32 v231, 64, v224
	v_max3_f32 v200, v200, v140, v156
	v_xor_b32_e32 v202, 32, v224
	v_add_u32_e32 v231, 64, v231
	v_max3_f32 v200, v200, v141, v157
	v_cmp_lt_i32_e32 vcc, v202, v231
	v_max3_f32 v200, v200, v142, v158
	v_max3_f32 v200, v200, v143, v159
	v_cndmask_b32_e32 v202, v224, v202, vcc
	v_lshlrev_b32_e32 v202, 2, v202
	ds_bpermute_b32 v202, v202, v200
	s_waitcnt lgkmcnt(0)
	v_max_f32_e32 v202, v202, v202
	v_max_f32_e32 v200, v200, v202
	v_mul_f32_e32 v200, 0x3e38aa3b, v200
	v_max_f32_e32 v202, v228, v228
	v_max_f32_e32 v200, v202, v200
	v_sub_f32_e32 v202, v200, v228
	v_cmp_lt_f32_e32 vcc, 4.0, v202
	s_nop 1
	v_cndmask_b32_e32 v200, v228, v200, vcc
	v_sub_f32_e32 v202, v228, v200
	v_exp_f32_e32 v202, v202
	s_nop 0
	v_cmp_neq_f32_e32 vcc, 1.0, v202
	s_cbranch_vccz .LBB0_1167
	v_pk_mul_f32 v[78:79], v[78:79], v[202:203] op_sel_hi:[1,0]
	v_pk_mul_f32 v[76:77], v[76:77], v[202:203] op_sel_hi:[1,0]
	v_pk_mul_f32 v[74:75], v[74:75], v[202:203] op_sel_hi:[1,0]
	v_pk_mul_f32 v[72:73], v[72:73], v[202:203] op_sel_hi:[1,0]
	v_pk_mul_f32 v[70:71], v[70:71], v[202:203] op_sel_hi:[1,0]
	v_pk_mul_f32 v[68:69], v[68:69], v[202:203] op_sel_hi:[1,0]
	v_pk_mul_f32 v[66:67], v[66:67], v[202:203] op_sel_hi:[1,0]
	v_pk_mul_f32 v[64:65], v[64:65], v[202:203] op_sel_hi:[1,0]
	v_pk_mul_f32 v[62:63], v[62:63], v[202:203] op_sel_hi:[1,0]
	v_pk_mul_f32 v[60:61], v[60:61], v[202:203] op_sel_hi:[1,0]
	v_pk_mul_f32 v[58:59], v[58:59], v[202:203] op_sel_hi:[1,0]
	v_pk_mul_f32 v[56:57], v[56:57], v[202:203] op_sel_hi:[1,0]
	v_pk_mul_f32 v[54:55], v[54:55], v[202:203] op_sel_hi:[1,0]
	v_pk_mul_f32 v[52:53], v[52:53], v[202:203] op_sel_hi:[1,0]
	v_pk_mul_f32 v[50:51], v[50:51], v[202:203] op_sel_hi:[1,0]
	v_pk_mul_f32 v[48:49], v[48:49], v[202:203] op_sel_hi:[1,0]
	v_pk_mul_f32 v[46:47], v[46:47], v[202:203] op_sel_hi:[1,0]
	v_pk_mul_f32 v[44:45], v[44:45], v[202:203] op_sel_hi:[1,0]
	v_pk_mul_f32 v[42:43], v[42:43], v[202:203] op_sel_hi:[1,0]
	v_pk_mul_f32 v[40:41], v[40:41], v[202:203] op_sel_hi:[1,0]
	v_pk_mul_f32 v[38:39], v[38:39], v[202:203] op_sel_hi:[1,0]
	v_pk_mul_f32 v[36:37], v[36:37], v[202:203] op_sel_hi:[1,0]
	v_pk_mul_f32 v[34:35], v[34:35], v[202:203] op_sel_hi:[1,0]
	v_pk_mul_f32 v[32:33], v[32:33], v[202:203] op_sel_hi:[1,0]
	v_pk_mul_f32 v[14:15], v[14:15], v[202:203] op_sel_hi:[1,0]
	v_pk_mul_f32 v[12:13], v[12:13], v[202:203] op_sel_hi:[1,0]
	v_pk_mul_f32 v[10:11], v[10:11], v[202:203] op_sel_hi:[1,0]
	v_pk_mul_f32 v[8:9], v[8:9], v[202:203] op_sel_hi:[1,0]
	v_pk_mul_f32 v[6:7], v[6:7], v[202:203] op_sel_hi:[1,0]
	v_pk_mul_f32 v[4:5], v[4:5], v[202:203] op_sel_hi:[1,0]
	v_pk_mul_f32 v[2:3], v[2:3], v[202:203] op_sel_hi:[1,0]
	v_pk_mul_f32 v[0:1], v[0:1], v[202:203] op_sel_hi:[1,0]

; template <int NS, int SI>
; __device__ __forceinline__ void attn_stream(const unsigned char* kbase, const unsigned char* vbase, const unsigned char* q_rd, bool mask_tail, int last_valid, int hh, float sc,
;                                             f32x16 (&O)[4], float& mrun, float& lrun) {
;     ...
;     float mx = __builtin_amdgcn_fmed3f(S0[0], S1[0], __builtin_inff());
; #pragma unroll
;     for (int r = 1; r < 16; ++r) { mx = __builtin_amdgcn_fmed3f(mx, S0[r], __builtin_inff()); mx = __builtin_amdgcn_fmed3f(mx, S1[r], __builtin_inff()); }
;     mx = fmaxf(mx, __shfl_xor(mx, 32));
;     const float mn = fmaxf(mrun, mx * sc);
;     const float alpha = __builtin_amdgcn_exp2f(mrun - mn);
;     mrun = mn;
;     f32x2 ls2 = {0.f, 0.f};
;     const f32x2 sc2 = {sc, sc}, mn2 = {mn, mn};
; #pragma unroll
;     for (int r = 0; r < 16; r += 2) {
;         const f32x2 t0 = (f32x2){S0[r], S0[r + 1]} * sc2 - mn2, t1 = (f32x2){S1[r], S1[r + 1]} * sc2 - mn2;
;         const f32x2 p0 = {__builtin_amdgcn_exp2f(t0.x), __builtin_amdgcn_exp2f(t0.y)}, p1 = {__builtin_amdgcn_exp2f(t1.x), __builtin_amdgcn_exp2f(t1.y)};
;         S0[r] = p0.x; S0[r + 1] = p0.y; S1[r] = p1.x; S1[r + 1] = p1.y; ls2 += p0 + p1;
;     }
;     lrun = lrun * alpha + (ls2.x + ls2.y);
;     if (__any(alpha != 1.0f)) {
; #pragma unroll
;         for (int d = 0; d < 4; ++d) O[d] = O[d] * alpha;
;     }
.LBB0_1177:
	s_nop 9
	v_max_f32_e32 v200, v144, v144
	v_max_f32_e32 v202, v128, v128
	v_max_f32_e32 v200, v202, v200
	v_max3_f32 v200, v200, v129, v145
	v_max3_f32 v200, v200, v130, v146
	v_max3_f32 v200, v200, v131, v147
	v_max3_f32 v200, v200, v132, v148
	v_max3_f32 v200, v200, v133, v149
	v_max3_f32 v200, v200, v134, v150
	v_max3_f32 v200, v200, v135, v151
	v_max3_f32 v200, v200, v136, v152
	v_max3_f32 v200, v200, v137, v153
	v_max3_f32 v200, v200, v138, v154
	v_max3_f32 v200, v200, v139, v155
	v_and_b32_e32 v230, 64, v224
	v_max3_f32 v200, v200, v140, v156
	v_xor_b32_e32 v202, 32, v224
	v_add_u32_e32 v230, 64, v230
	v_max3_f32 v200, v200, v141, v157
	v_cmp_lt_i32_e32 vcc, v202, v230
	v_max3_f32 v200, v200, v142, v158
	v_max3_f32 v200, v200, v143, v159
	v_cndmask_b32_e32 v202, v224, v202, vcc
	v_lshlrev_b32_e32 v202, 2, v202
	ds_bpermute_b32 v202, v202, v200
	s_waitcnt lgkmcnt(0)
	v_max_f32_e32 v202, v202, v202
	v_max_f32_e32 v200, v200, v202
	v_mul_f32_e32 v200, 0x3e38aa3b, v200
	v_max_f32_e32 v202, v229, v229
	v_max_f32_e32 v200, v202, v200
	v_sub_f32_e32 v202, v200, v229
	v_cmp_lt_f32_e32 vcc, 4.0, v202
	s_nop 1
	v_cndmask_b32_e32 v200, v229, v200, vcc
	v_sub_f32_e32 v202, v229, v200
	v_exp_f32_e32 v202, v202
	s_nop 0
	v_cmp_neq_f32_e32 vcc, 1.0, v202
	s_cbranch_vccz .LBB0_1179
	v_pk_mul_f32 v[126:127], v[126:127], v[202:203] op_sel_hi:[1,0]
	v_pk_mul_f32 v[124:125], v[124:125], v[202:203] op_sel_hi:[1,0]
	v_pk_mul_f32 v[122:123], v[122:123], v[202:203] op_sel_hi:[1,0]
	v_pk_mul_f32 v[120:121], v[120:121], v[202:203] op_sel_hi:[1,0]
	v_pk_mul_f32 v[118:119], v[118:119], v[202:203] op_sel_hi:[1,0]
	v_pk_mul_f32 v[116:117], v[116:117], v[202:203] op_sel_hi:[1,0]
	v_pk_mul_f32 v[114:115], v[114:115], v[202:203] op_sel_hi:[1,0]
	v_pk_mul_f32 v[112:113], v[112:113], v[202:203] op_sel_hi:[1,0]
	v_pk_mul_f32 v[110:111], v[110:111], v[202:203] op_sel_hi:[1,0]
	v_pk_mul_f32 v[108:109], v[108:109], v[202:203] op_sel_hi:[1,0]
	v_pk_mul_f32 v[106:107], v[106:107], v[202:203] op_sel_hi:[1,0]
	v_pk_mul_f32 v[104:105], v[104:105], v[202:203] op_sel_hi:[1,0]
	v_pk_mul_f32 v[102:103], v[102:103], v[202:203] op_sel_hi:[1,0]
	v_pk_mul_f32 v[100:101], v[100:101], v[202:203] op_sel_hi:[1,0]
	v_pk_mul_f32 v[98:99], v[98:99], v[202:203] op_sel_hi:[1,0]
	v_pk_mul_f32 v[96:97], v[96:97], v[202:203] op_sel_hi:[1,0]
	v_pk_mul_f32 v[94:95], v[94:95], v[202:203] op_sel_hi:[1,0]
	v_pk_mul_f32 v[92:93], v[92:93], v[202:203] op_sel_hi:[1,0]
	v_pk_mul_f32 v[90:91], v[90:91], v[202:203] op_sel_hi:[1,0]
	v_pk_mul_f32 v[88:89], v[88:89], v[202:203] op_sel_hi:[1,0]
	v_pk_mul_f32 v[86:87], v[86:87], v[202:203] op_sel_hi:[1,0]
	v_pk_mul_f32 v[84:85], v[84:85], v[202:203] op_sel_hi:[1,0]
	v_pk_mul_f32 v[82:83], v[82:83], v[202:203] op_sel_hi:[1,0]
	v_pk_mul_f32 v[80:81], v[80:81], v[202:203] op_sel_hi:[1,0]
	v_pk_mul_f32 v[30:31], v[30:31], v[202:203] op_sel_hi:[1,0]
	v_pk_mul_f32 v[28:29], v[28:29], v[202:203] op_sel_hi:[1,0]
	v_pk_mul_f32 v[26:27], v[26:27], v[202:203] op_sel_hi:[1,0]
	v_pk_mul_f32 v[24:25], v[24:25], v[202:203] op_sel_hi:[1,0]
	v_pk_mul_f32 v[22:23], v[22:23], v[202:203] op_sel_hi:[1,0]
	v_pk_mul_f32 v[20:21], v[20:21], v[202:203] op_sel_hi:[1,0]
	v_pk_mul_f32 v[18:19], v[18:19], v[202:203] op_sel_hi:[1,0]
	v_pk_mul_f32 v[16:17], v[16:17], v[202:203] op_sel_hi:[1,0]
